# GEMM 256x256 loops: LDS stash moved into the MFMA stream and global prefetch run two k-tiles ahead (issue block after last MFMA group, second k-tile issued in prologue)
# speedup vs baseline: 1.0269x; 1.0269x over previous
; template <int EPI, bool RSQ>
; DI void gemm_phase8(const Params& p, int l, const u16* __restrict__ A, int lda, const u16* __restrict__ Bt, int K,
;                    int ntiles_n, int gofs, char* smem, bool latonly = false) {
;     ...
;   unsigned LAo = (unsigned)((mt * 256 + srow) * lda + sch * 8) * 2u;
;   unsigned LBo = (unsigned)((nt * 256 + srow) * K + sch * 8) * 2u;
;   const unsigned strideA = (unsigned)(64 * lda) * 2u, strideB = (unsigned)(64 * K) * 2u;
;   auto issue = [&](u32x4 (&qa)[4], u32x4 (&qb)[4]) {
; #pragma unroll
;     for (int i = 0; i < 4; ++i) {
;       qa[i] = *(const u32x4*)((const char*)A + (LAo + i * strideA + (unsigned)Lkt * 128u));
;       qb[i] = *(const u32x4*)((const char*)Bt + (LBo + i * strideB + (unsigned)Lkt * 128u));
;     }
;     if (++Lkt == nk) {
;       Lkt = 0; Lt += nlb;
;       if (Lt < total) {
;         int a, b; decode(Lt, a, b);
;         LAo = (unsigned)((a * 256 + srow) * lda + sch * 8) * 2u;
;         LBo = (unsigned)((b * 256 + srow) * K + sch * 8) * 2u;
;       } else Lvalid = false;
;     }
;   };
;   float ssq[4] = {0.f, 0.f, 0.f, 0.f};
;   auto stash = [&](u32x4 (&qa)[4], u32x4 (&qb)[4], int stage) {
;     char* As = smem + stage * 73728;
;     char* Bs = As + 36864;
; #pragma unroll
;     for (int i = 0; i < 4; ++i) {
;       if (RSQ) { float f[8]; unpack8(qa[i], f);
; #pragma unroll
;         for (int e = 0; e < 8; ++e) ssq[i] = fmaf(f[e], f[e], ssq[i]); }
;       *(u32x4*)(As + (srow + 64 * i) * 144 + sch * 16) = qa[i];
;       *(u32x4*)(Bs + (srow + 64 * i) * 144 + sch * 16) = qb[i];
;     }
;   };
;   auto stash_part = [&](u32x4 (&qa)[4], u32x4 (&qb)[4], int stage, int i) {
;     char* As = smem + stage * 73728;
;     char* Bs = As + 36864;
;     if (RSQ) { float f[8]; unpack8(qa[i], f);
; #pragma unroll
;       for (int e = 0; e < 8; ++e) ssq[i] = fmaf(f[e], f[e], ssq[i]); }
;     *(u32x4*)(As + (srow + 64 * i) * 144 + sch * 16) = qa[i];
;     *(u32x4*)(Bs + (srow + 64 * i) * 144 + sch * 16) = qb[i];
;   };
;   u32x4 ra0[4], rb0[4], ra1[4], rb1[4];
;   f32x16 acc[4][2];
; #pragma unroll
;   for (int a = 0; a < 4; ++a)
; #pragma unroll
;     for (int b = 0; b < 2; ++b)
; #pragma unroll
;       for (int i = 0; i < 16; ++i) acc[a][b][i] = 0.f;
;   issue(ra0, rb0);
;   bool v1 = DEEP && Lvalid;
;   if (v1) issue(ra1, rb1);
;   stash(ra0, rb0, 0);
;   __syncthreads();
.LBB1_212:
	s_or_b64 exec, exec, s[0:1]
	v_readlane_b32 s2, v235, 55
	s_mul_i32 s1, s2, 0x1910000
	v_readlane_b32 s3, v235, 56
	s_mul_hi_u32 s0, s2, 0x1910000
	s_add_u32 s2, s52, s1
	s_addc_u32 s3, s53, s0
	v_readlane_b32 s0, v236, 45
	v_readlane_b32 s1, v236, 46
	v_writelane_b32 v235, s2, 59
	s_andn2_b64 vcc, exec, s[0:1]
	s_waitcnt lgkmcnt(0)
	v_writelane_b32 v235, s3, 60
	s_barrier
	s_cbranch_vccnz .LBB1_745
	v_mov_b32_e32 v0, v192
	v_readlane_b32 s0, v235, 21
	v_ashrrev_i32_e32 v2, 3, v0
	v_lshlrev_b32_e32 v3, 11, v2
	v_lshlrev_b32_e32 v4, 4, v0
	v_bfe_u32 v1, v0, 6, 2
	v_add_u32_e32 v5, s0, v3
	v_readlane_b32 s0, v235, 19
	v_ashrrev_i32_e32 v194, 8, v0
	v_and_b32_e32 v199, 31, v0
	v_bfe_u32 v200, v0, 5, 1
	v_and_b32_e32 v0, 0x70, v4
	v_add_u32_e32 v6, s0, v3
	v_or_b32_e32 v215, v5, v0
	v_or_b32_e32 v216, v6, v0
	v_readlane_b32 s0, v235, 59
	v_add_u32_e32 v4, 0x20000, v215
	global_load_dwordx4 v[128:131], v215, s[62:63]
	global_load_dwordx4 v[136:139], v4, s[62:63]
	v_readlane_b32 s1, v235, 60
	v_add_u32_e32 v4, 0x20000, v216
	v_mul_lo_u32 v2, v2, s47
	v_add3_u32 v201, 0, v2, v0
	v_lshl_or_b32 v2, v194, 7, v199
	v_mul_lo_u32 v202, v2, s47
	global_load_dwordx4 v[140:143], v4, s[0:1]
	v_add_u32_e32 v4, 0x40000, v215
	global_load_dwordx4 v[144:147], v4, s[62:63]
	v_add_u32_e32 v4, 0x40000, v216
	global_load_dwordx4 v[148:151], v4, s[0:1]
	v_add_u32_e32 v4, 0x60000, v215
	global_load_dwordx4 v[152:155], v4, s[62:63]
	v_add_u32_e32 v4, 0x60000, v216
	global_load_dwordx4 v[132:135], v216, s[0:1]
	global_load_dwordx4 v[156:159], v4, s[0:1]
	v_readlane_b32 s0, v235, 55
	v_lshl_or_b32 v2, v1, 6, v199
	v_or_b32_e32 v214, v3, v0
	v_readlane_b32 s1, v235, 56
	s_lshl_b32 s8, s0, 9
	v_mov_b32_e32 v0, 0
	v_readlane_b32 s11, v235, 17
	v_lshlrev_b32_e32 v203, 4, v200
	v_mul_u32_u24_e32 v213, 0x90, v2
	s_mov_b32 s12, 1
	v_lshlrev_b32_e32 v217, 1, v1
	s_addk_i32 s8, 0xfc60
	s_mov_b32 s9, 0
	s_mov_b64 s[0:1], -1
	s_mov_b32 s10, s11
	v_readlane_b32 s13, v235, 18
	v_readlane_b32 s14, v235, 20
	s_mov_b32 s15, 0
	v_mov_b32_e32 v1, v0
	v_mov_b32_e32 v2, v0
	v_mov_b32_e32 v3, v0
	v_mov_b32_e32 v4, v0
	v_mov_b32_e32 v5, v0
	v_mov_b32_e32 v6, v0
	v_mov_b32_e32 v7, v0
	v_mov_b32_e32 v8, v0
	v_mov_b32_e32 v9, v0
	v_mov_b32_e32 v10, v0
	v_mov_b32_e32 v11, v0
	v_mov_b32_e32 v12, v0
	v_mov_b32_e32 v13, v0
	v_mov_b32_e32 v14, v0
	v_mov_b32_e32 v15, v0
	v_mov_b32_e32 v64, v0
	v_mov_b32_e32 v65, v0
	v_mov_b32_e32 v66, v0
	v_mov_b32_e32 v67, v0
	v_mov_b32_e32 v68, v0
	v_mov_b32_e32 v69, v0
	v_mov_b32_e32 v70, v0
	v_mov_b32_e32 v71, v0
	v_mov_b32_e32 v72, v0
	v_mov_b32_e32 v73, v0
	v_mov_b32_e32 v74, v0
	v_mov_b32_e32 v75, v0
	v_mov_b32_e32 v76, v0
	v_mov_b32_e32 v77, v0
	v_mov_b32_e32 v78, v0
	v_mov_b32_e32 v79, v0
	v_mov_b32_e32 v16, v0
	v_mov_b32_e32 v17, v0
	v_mov_b32_e32 v18, v0
	v_mov_b32_e32 v19, v0
	v_mov_b32_e32 v20, v0
	v_mov_b32_e32 v21, v0
	v_mov_b32_e32 v22, v0
	v_mov_b32_e32 v23, v0
	v_mov_b32_e32 v24, v0
	v_mov_b32_e32 v25, v0
	v_mov_b32_e32 v26, v0
	v_mov_b32_e32 v27, v0
	v_mov_b32_e32 v28, v0
	v_mov_b32_e32 v29, v0
	v_mov_b32_e32 v30, v0
	v_mov_b32_e32 v31, v0
	v_mov_b32_e32 v80, v0
	v_mov_b32_e32 v81, v0
	v_mov_b32_e32 v82, v0
	v_mov_b32_e32 v83, v0
	v_mov_b32_e32 v84, v0
	v_mov_b32_e32 v85, v0
	v_mov_b32_e32 v86, v0
	v_mov_b32_e32 v87, v0
	v_mov_b32_e32 v88, v0
	v_mov_b32_e32 v89, v0
	v_mov_b32_e32 v90, v0
	v_mov_b32_e32 v91, v0
	v_mov_b32_e32 v92, v0
	v_mov_b32_e32 v93, v0
	v_mov_b32_e32 v94, v0
	v_mov_b32_e32 v95, v0
	v_mov_b32_e32 v32, v0
	v_mov_b32_e32 v33, v0
	v_mov_b32_e32 v34, v0
	v_mov_b32_e32 v35, v0
	v_mov_b32_e32 v36, v0
	v_mov_b32_e32 v37, v0
	v_mov_b32_e32 v38, v0
	v_mov_b32_e32 v39, v0
	v_mov_b32_e32 v40, v0
	v_mov_b32_e32 v41, v0
	v_mov_b32_e32 v42, v0
	v_mov_b32_e32 v43, v0
	v_mov_b32_e32 v44, v0
	v_mov_b32_e32 v45, v0
	v_mov_b32_e32 v46, v0
	v_mov_b32_e32 v47, v0
	v_mov_b32_e32 v96, v0
	v_mov_b32_e32 v97, v0
	v_mov_b32_e32 v98, v0
	v_mov_b32_e32 v99, v0
	v_mov_b32_e32 v100, v0
	v_mov_b32_e32 v101, v0
	v_mov_b32_e32 v102, v0
	v_mov_b32_e32 v103, v0
	v_mov_b32_e32 v104, v0
	v_mov_b32_e32 v105, v0
	v_mov_b32_e32 v106, v0
	v_mov_b32_e32 v107, v0
	v_mov_b32_e32 v108, v0
	v_mov_b32_e32 v109, v0
	v_mov_b32_e32 v110, v0
	v_mov_b32_e32 v111, v0
	v_mov_b32_e32 v48, v0
	v_mov_b32_e32 v49, v0
	v_mov_b32_e32 v50, v0
	v_mov_b32_e32 v51, v0
	v_mov_b32_e32 v52, v0
	v_mov_b32_e32 v53, v0
	v_mov_b32_e32 v54, v0
	v_mov_b32_e32 v55, v0
	v_mov_b32_e32 v56, v0
	v_mov_b32_e32 v57, v0
	v_mov_b32_e32 v58, v0
	v_mov_b32_e32 v59, v0
	v_mov_b32_e32 v60, v0
	v_mov_b32_e32 v61, v0
	v_mov_b32_e32 v62, v0
	v_mov_b32_e32 v63, v0
	v_mov_b32_e32 v112, v0
	v_mov_b32_e32 v113, v0
	v_mov_b32_e32 v114, v0
	v_mov_b32_e32 v115, v0
	v_mov_b32_e32 v116, v0
	v_mov_b32_e32 v117, v0
	v_mov_b32_e32 v118, v0
	v_mov_b32_e32 v119, v0
	s_waitcnt vmcnt(20)
	v_mov_b32_e32 v120, v0
	v_mov_b32_e32 v121, v0
	v_mov_b32_e32 v122, v0
	v_mov_b32_e32 v123, v0
	s_waitcnt vmcnt(19)
	v_mov_b32_e32 v124, v0
	v_mov_b32_e32 v125, v0
	v_mov_b32_e32 v126, v0
	v_mov_b32_e32 v127, v0
	s_waitcnt vmcnt(7)
	ds_write_b128 v201, v[128:131]
	s_waitcnt vmcnt(1)
	ds_write_b128 v201, v[132:135] offset:36864
	ds_write_b128 v201, v[136:139] offset:9216
	ds_write_b128 v201, v[140:143] offset:46080
	ds_write_b128 v201, v[144:147] offset:18432
	ds_write_b128 v201, v[148:151] offset:55296
	ds_write_b128 v201, v[152:155] offset:27648
	s_waitcnt vmcnt(0)
	ds_write_b128 v201, v[156:159] offset:64512
	s_lshl_b32 s0, s12, 7
	s_waitcnt vmcnt(1)
	v_add_u32_e32 v152, s0, v215
	s_waitcnt vmcnt(0)
	v_add_u32_e32 v156, s0, v216
	v_readlane_b32 s0, v235, 59
	v_readlane_b32 s1, v235, 60
	global_load_dwordx4 v[128:131], v152, s[62:63]
	v_add_u32_e32 v136, 0x20000, v152
	v_add_u32_e32 v140, 0x20000, v156
	v_add_u32_e32 v144, 0x40000, v152
	v_add_u32_e32 v148, 0x40000, v156
	global_load_dwordx4 v[132:135], v156, s[0:1]
	v_add_u32_e32 v152, 0x60000, v152
	v_add_u32_e32 v156, 0x60000, v156
	global_load_dwordx4 v[136:139], v136, s[62:63]
	s_add_i32 s12, s12, 1
	global_load_dwordx4 v[140:143], v140, s[0:1]
	s_cmp_lg_u32 s12, 16
	global_load_dwordx4 v[144:147], v144, s[62:63]
	s_nop 0
	global_load_dwordx4 v[148:151], v148, s[0:1]
	s_nop 0
	global_load_dwordx4 v[152:155], v152, s[62:63]
	s_nop 0
	global_load_dwordx4 v[156:159], v156, s[0:1]
	s_mov_b64 s[0:1], -1
	s_waitcnt lgkmcnt(0)
	s_barrier
	s_branch .LBB1_215

; template <int EPI, bool RSQ>
; DI void gemm_phase8(const Params& p, int l, const u16* __restrict__ A, int lda, const u16* __restrict__ Bt, int K,
;                    int ntiles_n, int gofs, char* smem, bool latonly = false) {
;     ...
;   auto issue = [&](u32x4 (&qa)[4], u32x4 (&qb)[4]) {
; #pragma unroll
;     for (int i = 0; i < 4; ++i) {
;       qa[i] = *(const u32x4*)((const char*)A + (LAo + i * strideA + (unsigned)Lkt * 128u));
;     ...
;     {
;       const char* As = smem + cur * 73728;
;       const char* Bs = As + 36864;
;       const char* ap = As + (wr * 128 + lr) * 144 + lh * 16;
;       const char* bp = Bs + (wc * 64 + lr) * 144 + lh * 16;
;       bf16x8 fa[3][2], fb[2][2];
;       fa[0][0] = *(const bf16x8*)(ap);
;       fa[0][1] = *(const bf16x8*)(ap + 32 * 144);
;       fb[0][0] = *(const bf16x8*)(bp);
;       fb[0][1] = *(const bf16x8*)(bp + 32 * 144);
;       fa[1][0] = *(const bf16x8*)(ap + 2 * 32 * 144);
;       fa[1][1] = *(const bf16x8*)(ap + 3 * 32 * 144);
;       fb[1][0] = *(const bf16x8*)(bp + 32);
;       fb[1][1] = *(const bf16x8*)(bp + 32 * 144 + 32);
; #pragma unroll
;       for (int u = 0; u < 8; ++u) {
;         const int ks = u >> 1, hf = u & 1, ca = u % 3, cb = ks & 1;
;         if (u + 2 < 8) {
;           const int ks2 = (u + 2) >> 1, hf2 = (u + 2) & 1, cn = (u + 2) % 3;
;           fa[cn][0] = *(const bf16x8*)(ap + (2 * hf2) * 32 * 144 + ks2 * 32);
;           fa[cn][1] = *(const bf16x8*)(ap + (2 * hf2 + 1) * 32 * 144 + ks2 * 32);
;         }
;         __builtin_amdgcn_sched_barrier(0);
;         __builtin_amdgcn_s_setprio(1);
;         acc[2 * hf][0] = MFMA32(fa[ca][0], fb[cb][0], acc[2 * hf][0]);
;         acc[2 * hf][1] = MFMA32(fa[ca][0], fb[cb][1], acc[2 * hf][1]);
;         acc[2 * hf + 1][0] = MFMA32(fa[ca][1], fb[cb][0], acc[2 * hf + 1][0]);
;         acc[2 * hf + 1][1] = MFMA32(fa[ca][1], fb[cb][1], acc[2 * hf + 1][1]);
;         __builtin_amdgcn_s_setprio(0);
;         __builtin_amdgcn_sched_barrier(0);
;         if (u == 0) {
;           if (Lset_valid) issue(La, Lb);
;           __builtin_amdgcn_sched_barrier(0);
;         }
;         if (hf == 1 && ks + 2 < 4) {
;           fb[cb][0] = *(const bf16x8*)(bp + (ks + 2) * 32);
;           fb[cb][1] = *(const bf16x8*)(bp + 32 * 144 + (ks + 2) * 32);
;           __builtin_amdgcn_sched_barrier(0);
;         }
;       }
.LBB1_215:
	s_mul_i32 s2, s9, 0x12000
	s_add_i32 s2, s2, 0
	v_add_u32_e32 v160, s2, v202
	v_add_u32_e32 v218, v160, v203
	v_add_u32_e32 v160, s2, v213
	v_add_u32_e32 v219, v160, v203
	ds_read_b128 v[176:179], v219 offset:36864
	ds_read_b128 v[160:163], v219 offset:36896
	ds_read_b128 v[188:191], v218 offset:9216
	ds_read_b128 v[180:183], v218 offset:13824
	ds_read_b128 v[184:187], v219 offset:41472
	ds_read_b128 v[164:167], v219 offset:41504
	ds_read_b128 v[220:223], v218
	ds_read_b128 v[172:175], v218 offset:32
	ds_read_b128 v[224:227], v218 offset:4608
	ds_read_b128 v[168:171], v218 offset:4640
	v_subrev_u32_e32 v238, s2, v201
	v_add_u32_e32 v238, 0x12000, v238
	s_setprio 1
	s_waitcnt lgkmcnt(3)
	v_mfma_f32_32x32x16_bf16 v[112:127], v[220:223], v[176:179], v[112:127]
	v_mfma_f32_32x32x16_bf16 v[48:63], v[220:223], v[184:187], v[48:63]
	s_waitcnt lgkmcnt(1)
	v_mfma_f32_32x32x16_bf16 v[96:111], v[224:227], v[176:179], v[96:111]
	v_mfma_f32_32x32x16_bf16 v[32:47], v[224:227], v[184:187], v[32:47]
	s_setprio 0
.LBB1_220:
	ds_read_b128 v[220:223], v218 offset:9248
	ds_read_b128 v[224:227], v218 offset:13856
	s_setprio 1
	v_mfma_f32_32x32x16_bf16 v[80:95], v[188:191], v[176:179], v[80:95]
	v_mfma_f32_32x32x16_bf16 v[16:31], v[188:191], v[184:187], v[16:31]
	v_mfma_f32_32x32x16_bf16 v[64:79], v[180:183], v[176:179], v[64:79]
	v_mfma_f32_32x32x16_bf16 v[0:15], v[180:183], v[184:187], v[0:15]
	s_setprio 0
	ds_read_b128 v[176:179], v219 offset:36928
	ds_read_b128 v[180:183], v219 offset:41536
	ds_read_b128 v[184:187], v218 offset:64
	ds_read_b128 v[188:191], v218 offset:4672
	s_setprio 1
	v_mfma_f32_32x32x16_bf16 v[112:127], v[172:175], v[160:163], v[112:127]
	v_mfma_f32_32x32x16_bf16 v[48:63], v[172:175], v[164:167], v[48:63]
	s_waitcnt lgkmcnt(6)
	v_mfma_f32_32x32x16_bf16 v[96:111], v[168:171], v[160:163], v[96:111]
	v_mfma_f32_32x32x16_bf16 v[32:47], v[168:171], v[164:167], v[32:47]
	s_setprio 0
	ds_read_b128 v[168:171], v218 offset:9280
	ds_read_b128 v[172:175], v218 offset:13888
	s_setprio 1
	s_waitcnt lgkmcnt(7)
	v_mfma_f32_32x32x16_bf16 v[80:95], v[220:223], v[160:163], v[80:95]
	v_mfma_f32_32x32x16_bf16 v[16:31], v[220:223], v[164:167], v[16:31]
	s_waitcnt lgkmcnt(6)
	v_mfma_f32_32x32x16_bf16 v[64:79], v[224:227], v[160:163], v[64:79]
	v_mfma_f32_32x32x16_bf16 v[0:15], v[224:227], v[164:167], v[0:15]
	s_setprio 0
	ds_read_b128 v[160:163], v219 offset:36960
	ds_read_b128 v[164:167], v219 offset:41568
	ds_read_b128 v[220:223], v218 offset:96
	ds_read_b128 v[224:227], v218 offset:4704
	s_setprio 1
	s_waitcnt lgkmcnt(7)
	v_mfma_f32_32x32x16_bf16 v[112:127], v[184:187], v[176:179], v[112:127]
	v_mfma_f32_32x32x16_bf16 v[48:63], v[184:187], v[180:183], v[48:63]
	s_waitcnt lgkmcnt(6)
	v_mfma_f32_32x32x16_bf16 v[96:111], v[188:191], v[176:179], v[96:111]
	v_mfma_f32_32x32x16_bf16 v[32:47], v[188:191], v[180:183], v[32:47]
	s_setprio 0
	ds_read_b128 v[184:187], v218 offset:9312
	ds_read_b128 v[188:191], v218 offset:13920
	s_waitcnt vmcnt(6)
	ds_write_b128 v238, v[128:131]
	ds_write_b128 v238, v[132:135] offset:36864
	s_setprio 1
	s_waitcnt lgkmcnt(9)
	v_mfma_f32_32x32x16_bf16 v[80:95], v[168:171], v[176:179], v[80:95]
	v_mfma_f32_32x32x16_bf16 v[16:31], v[168:171], v[180:183], v[16:31]
	s_waitcnt lgkmcnt(8)
	v_mfma_f32_32x32x16_bf16 v[64:79], v[172:175], v[176:179], v[64:79]
	v_mfma_f32_32x32x16_bf16 v[0:15], v[172:175], v[180:183], v[0:15]
	s_setprio 0
	s_waitcnt vmcnt(3)
	ds_write_b128 v238, v[136:139] offset:9216
	ds_write_b128 v238, v[140:143] offset:46080
	ds_write_b128 v238, v[144:147] offset:18432
	s_setprio 1
	s_waitcnt lgkmcnt(8)
	v_mfma_f32_32x32x16_bf16 v[112:127], v[220:223], v[160:163], v[112:127]
	v_mfma_f32_32x32x16_bf16 v[48:63], v[220:223], v[164:167], v[48:63]
	s_waitcnt lgkmcnt(7)
	v_mfma_f32_32x32x16_bf16 v[96:111], v[224:227], v[160:163], v[96:111]
	v_mfma_f32_32x32x16_bf16 v[32:47], v[224:227], v[164:167], v[32:47]
	s_setprio 0
	s_waitcnt vmcnt(0)
	ds_write_b128 v238, v[148:151] offset:55296
	ds_write_b128 v238, v[152:155] offset:27648
	ds_write_b128 v238, v[156:159] offset:64512
	s_setprio 1
	s_waitcnt lgkmcnt(9)
	v_mfma_f32_32x32x16_bf16 v[80:95], v[184:187], v[160:163], v[80:95]
	v_mfma_f32_32x32x16_bf16 v[16:31], v[184:187], v[164:167], v[16:31]
	s_waitcnt lgkmcnt(8)
	v_mfma_f32_32x32x16_bf16 v[64:79], v[188:191], v[160:163], v[64:79]
	v_mfma_f32_32x32x16_bf16 v[0:15], v[188:191], v[164:167], v[0:15]
	s_setprio 0
	v_cndmask_b32_e64 v220, 0, 1, s[0:1]
	v_cmp_ne_u32_e64 s[40:41], 1, v220
	s_andn2_b64 vcc, exec, s[0:1]
	s_mov_b64 s[0:1], 0
	s_cbranch_vccnz .Lgemm_issue_done_1
	s_lshl_b32 s0, s12, 7
	s_waitcnt vmcnt(1)
	v_add_u32_e32 v152, s0, v215
	s_waitcnt vmcnt(0)
	v_add_u32_e32 v156, s0, v216
	v_readlane_b32 s0, v235, 59
	v_readlane_b32 s1, v235, 60
	global_load_dwordx4 v[128:131], v152, s[62:63]
	v_add_u32_e32 v136, 0x20000, v152
	v_add_u32_e32 v140, 0x20000, v156
	v_add_u32_e32 v144, 0x40000, v152
	v_add_u32_e32 v148, 0x40000, v156
	global_load_dwordx4 v[132:135], v156, s[0:1]
	v_add_u32_e32 v152, 0x60000, v152
	v_add_u32_e32 v156, 0x60000, v156
	global_load_dwordx4 v[136:139], v136, s[62:63]
	s_add_i32 s12, s12, 1
	global_load_dwordx4 v[140:143], v140, s[0:1]
	s_cmp_lg_u32 s12, 16
	global_load_dwordx4 v[144:147], v144, s[62:63]
	s_nop 0
	global_load_dwordx4 v[148:151], v148, s[0:1]
	s_nop 0
	global_load_dwordx4 v[152:155], v152, s[62:63]
	s_nop 0
	global_load_dwordx4 v[156:159], v156, s[0:1]
	s_mov_b64 s[0:1], -1
	s_cbranch_scc1 .Lgemm_issue_done_1
	v_readlane_b32 s0, v236, 44
	s_add_i32 s10, s10, s0
	s_cmpk_gt_i32 s10, 0x175
	s_mov_b64 s[0:1], 0
	s_cbranch_scc1 .LBB1_219
	s_mul_hi_i32 s0, s10, 0x2e8ba2e9
	s_lshr_b32 s1, s0, 31
	s_ashr_i32 s0, s0, 4
	s_add_i32 s0, s0, s1
	s_lshl_b32 s1, s0, 3
	s_sub_i32 s2, 34, s1
	s_min_u32 s2, s2, 8
	v_cvt_f32_ubyte0_e32 v215, s2
	v_rcp_iflag_f32_e32 v215, v215
	s_sub_i32 s5, 0, s2
	s_mulk_i32 s0, 0xffa8
	s_add_i32 s0, s0, s10
	v_mul_f32_e32 v215, 0x4f7ffffe, v215
	v_cvt_u32_f32_e32 v215, v215
	s_abs_i32 s4, s0
	s_ashr_i32 s3, s0, 31
	v_readfirstlane_b32 s6, v215
	s_mul_i32 s5, s5, s6
	s_mul_hi_u32 s5, s6, s5
	s_add_i32 s6, s6, s5
	s_mul_hi_u32 s5, s4, s6
	s_mul_i32 s6, s5, s2
	s_sub_i32 s4, s4, s6
	s_add_i32 s6, s5, 1
	s_sub_i32 s7, s4, s2
	s_cmp_ge_u32 s4, s2
	s_cselect_b32 s5, s6, s5
	s_cselect_b32 s4, s7, s4
	s_add_i32 s6, s5, 1
	s_cmp_ge_u32 s4, s2
	s_cselect_b32 s4, s6, s5
	s_xor_b32 s4, s4, s3
	s_sub_i32 s3, s4, s3
	v_readlane_b32 s4, v236, 54
	s_add_i32 s1, s1, s4
	s_mul_i32 s2, s3, s2
	s_add_i32 s1, s1, s0
	s_sub_i32 s0, s1, s2
	v_lshl_add_u32 v215, s0, 19, v214
	v_lshl_add_u32 v216, s3, 19, v214
	s_mov_b64 s[0:1], -1

; template <int EPI, int MB, int NWC>
; DI void gemm_epi(const Params& p, int l, f32x16 (&acc)[MB][2], const float* rs, int mt, int nt, int gofs,
;                  int wr, int wc, int lr, int lh) {
;     ...
; #pragma unroll
;     for (int nb = 0; nb < 2; ++nb) {
;       const int cblk = nt * (NWC * 2) + wc * 2 + nb;
;       const int col = cblk * 32 + lr;
;       const int kind = (cblk >= 21 && cblk < 29) ? 1 : ((cblk >= 29 && cblk < 45) ? 2 : 0);
;       float oml = 0.f;
;       if (kind == 2) oml = 1.f - p.lbt[l * 512 + (col - 928)];
; template <int EPI, bool RSQ>
; DI void gemm_phase8(const Params& p, int l, const u16* __restrict__ A, int lda, const u16* __restrict__ Bt, int K,
;                    int ntiles_n, int gofs, char* smem, bool latonly = false) {
;     ...
;     if (last) {
;       if (RSQ) {
; #pragma unroll
;         for (int i = 0; i < 4; ++i) {
;           float v = ssq[i];
;           v += dpp_f<0xB1>(v); v += dpp_f<0x4E>(v); v += dpp_f<0x141>(v);
;           if (sch == 0) rs[srow + 64 * i] = rsqrtf(v / (float)K + 1e-6f);
;           ssq[i] = 0.f;
;         }
;         __syncthreads();
;       }
;       gemm_epi<EPI, 4, 4>(p, l, acc, rs, mt, nt, gofs, wr, wc, lr, lh);
.Lgemm_issue_done_1:
	s_cmp_lg_u32 s15, 15
	s_cselect_b64 s[4:5], -1, 0
	s_and_b64 vcc, exec, s[4:5]
	s_cbranch_vccnz .LBB1_738
	v_lshl_or_b32 v161, s13, 3, v217
	v_mov_b32_e32 v160, v199
	v_lshlrev_b32_e32 v162, 5, v161
	v_subrev_u32_e32 v166, 29, v161
	v_mov_b32_e32 v164, v200
	v_mov_b32_e32 v165, v194
	v_add_u32_e32 v163, v160, v162
	v_cmp_gt_u32_e32 vcc, 16, v166
	v_mov_b32_e32 v179, 0
	s_and_saveexec_b64 s[2:3], vcc
	s_cbranch_execz .LBB1_223
	v_add_u32_e32 v168, s8, v163
	v_ashrrev_i32_e32 v169, 31, v168
	v_lshl_add_u64 v[168:169], v[168:169], 2, s[58:59]
	global_load_dword v167, v[168:169], off
	s_waitcnt vmcnt(0)
	v_sub_f32_e32 v179, 1.0, v167

; template <int EPI, bool RSQ>
; DI void gemm_phase8(const Params& p, int l, const u16* __restrict__ A, int lda, const u16* __restrict__ Bt, int K,
;                    int ntiles_n, int gofs, char* smem, bool latonly = false) {
;     ...
;     if (Sset_valid) stash(Sa, Sb, cur ^ 1);
;     __syncthreads();
;     cur ^= 1;
;     if (last) {
;       t += nlb;
;       if (t >= total) return false;
;       decode(t, mt, nt);
;       kt = 0;
;     } else {
;       ++kt;
;     }
;     return true;
.LBB1_738:
	s_and_b64 vcc, exec, s[40:41]
	s_xor_b32 s9, s9, 1
	s_cbranch_vccnz .LBB1_740
.LBB1_740:
	s_mov_b64 s[2:3], -1
	s_and_b64 vcc, exec, s[4:5]
	s_waitcnt lgkmcnt(0)
	s_barrier
	s_cbranch_vccz .LBB1_742
	s_add_i32 s15, s15, 1
	s_mov_b64 s[2:3], 0

; template <int EPI, bool RSQ>
; DI void gemm_phase8(const Params& p, int l, const u16* __restrict__ A, int lda, const u16* __restrict__ Bt, int K,
;                    int ntiles_n, int gofs, char* smem, bool latonly = false) {
;     ...
;   unsigned LAo = (unsigned)((mt * 256 + srow) * lda + sch * 8) * 2u;
;   unsigned LBo = (unsigned)((nt * 256 + srow) * K + sch * 8) * 2u;
;   const unsigned strideA = (unsigned)(64 * lda) * 2u, strideB = (unsigned)(64 * K) * 2u;
;   auto issue = [&](u32x4 (&qa)[4], u32x4 (&qb)[4]) {
; #pragma unroll
;     for (int i = 0; i < 4; ++i) {
;       qa[i] = *(const u32x4*)((const char*)A + (LAo + i * strideA + (unsigned)Lkt * 128u));
;       qb[i] = *(const u32x4*)((const char*)Bt + (LBo + i * strideB + (unsigned)Lkt * 128u));
;     }
;     if (++Lkt == nk) {
;       Lkt = 0; Lt += nlb;
;       if (Lt < total) {
;         int a, b; decode(Lt, a, b);
;         LAo = (unsigned)((a * 256 + srow) * lda + sch * 8) * 2u;
;         LBo = (unsigned)((b * 256 + srow) * K + sch * 8) * 2u;
;       } else Lvalid = false;
;     }
;   };
;   float ssq[4] = {0.f, 0.f, 0.f, 0.f};
;   auto stash = [&](u32x4 (&qa)[4], u32x4 (&qb)[4], int stage) {
;     char* As = smem + stage * 73728;
;     char* Bs = As + 36864;
; #pragma unroll
;     for (int i = 0; i < 4; ++i) {
;       if (RSQ) { float f[8]; unpack8(qa[i], f);
; #pragma unroll
;         for (int e = 0; e < 8; ++e) ssq[i] = fmaf(f[e], f[e], ssq[i]); }
;       *(u32x4*)(As + (srow + 64 * i) * 144 + sch * 16) = qa[i];
;       *(u32x4*)(Bs + (srow + 64 * i) * 144 + sch * 16) = qb[i];
;     }
;   };
;   auto stash_part = [&](u32x4 (&qa)[4], u32x4 (&qb)[4], int stage, int i) {
;     char* As = smem + stage * 73728;
;     char* Bs = As + 36864;
;     if (RSQ) { float f[8]; unpack8(qa[i], f);
; #pragma unroll
;       for (int e = 0; e < 8; ++e) ssq[i] = fmaf(f[e], f[e], ssq[i]); }
;     *(u32x4*)(As + (srow + 64 * i) * 144 + sch * 16) = qa[i];
;     *(u32x4*)(Bs + (srow + 64 * i) * 144 + sch * 16) = qb[i];
;   };
;   u32x4 ra0[4], rb0[4], ra1[4], rb1[4];
;   f32x16 acc[4][2];
; #pragma unroll
;   for (int a = 0; a < 4; ++a)
; #pragma unroll
;     for (int b = 0; b < 2; ++b)
; #pragma unroll
;       for (int i = 0; i < 16; ++i) acc[a][b][i] = 0.f;
;   issue(ra0, rb0);
;   bool v1 = DEEP && Lvalid;
;   if (v1) issue(ra1, rb1);
;   stash(ra0, rb0, 0);
;   __syncthreads();
.LBB1_1298:
	v_readlane_b32 s6, v235, 59
	v_ashrrev_i32_e32 v1, 3, v0
	v_readlane_b32 s7, v235, 60
	s_add_u32 s6, s6, 0x690000
	v_readlane_b32 s3, v236, 54
	s_addc_u32 s7, s7, 0
	v_lshlrev_b32_e32 v2, 4, v0
	v_lshlrev_b32_e32 v17, 11, v1
	s_add_i32 s23, s2, s3
	v_and_b32_e32 v16, 0x70, v2
	v_lshl_add_u32 v2, s22, 19, v17
	v_lshl_add_u32 v3, s23, 19, v17
	v_or_b32_e32 v202, v2, v16
	v_or_b32_e32 v214, v3, v16
	v_add_u32_e32 v2, 0x60000, v202
	v_add_u32_e32 v3, 0x60000, v214
	v_add_u32_e32 v4, 0x40000, v202
	v_add_u32_e32 v5, 0x40000, v214
	v_add_u32_e32 v6, 0x20000, v202
	v_add_u32_e32 v7, 0x20000, v214
	global_load_dwordx4 v[128:131], v214, s[62:63]
	global_load_dwordx4 v[132:135], v202, s[6:7]
	global_load_dwordx4 v[136:139], v7, s[62:63]
	global_load_dwordx4 v[140:143], v6, s[6:7]
	global_load_dwordx4 v[144:147], v5, s[62:63]
	global_load_dwordx4 v[148:151], v4, s[6:7]
	global_load_dwordx4 v[152:155], v3, s[62:63]
	global_load_dwordx4 v[156:159], v2, s[6:7]
	v_ashrrev_i32_e32 v194, 8, v0
	v_and_b32_e32 v200, 31, v0
	v_and_b32_e32 v199, 0xc0, v0
	v_bfe_u32 v201, v0, 5, 1
	v_and_b32_e32 v2, 0xdf, v0
	v_mov_b32_e32 v0, 0
	v_readlane_b32 s35, v235, 17
	v_mul_lo_u32 v18, v1, s47
	v_lshl_or_b32 v19, v194, 7, v200
	s_mov_b32 s31, 0
	s_mov_b64 s[8:9], -1
	s_mov_b32 s37, 1
	s_mov_b32 s34, s35
	s_mov_b32 s36, 0
	v_lshlrev_b32_e32 v203, 4, v201
	v_mul_u32_u24_e32 v213, 0x90, v2
	v_mov_b32_e32 v1, v0
	v_mov_b32_e32 v2, v0
	v_mov_b32_e32 v3, v0
	v_mov_b32_e32 v4, v0
	v_mov_b32_e32 v5, v0
	v_mov_b32_e32 v6, v0
	v_mov_b32_e32 v7, v0
	v_mov_b32_e32 v8, v0
	v_mov_b32_e32 v9, v0
	v_mov_b32_e32 v10, v0
	v_mov_b32_e32 v11, v0
	v_mov_b32_e32 v12, v0
	v_mov_b32_e32 v13, v0
	v_mov_b32_e32 v14, v0
	v_mov_b32_e32 v15, v0
	v_mov_b32_e32 v64, v0
	v_mov_b32_e32 v65, v0
	v_mov_b32_e32 v66, v0
	v_mov_b32_e32 v67, v0
	v_mov_b32_e32 v68, v0
	v_mov_b32_e32 v69, v0
	v_mov_b32_e32 v70, v0
	v_mov_b32_e32 v71, v0
	v_mov_b32_e32 v72, v0
	v_mov_b32_e32 v73, v0
	v_mov_b32_e32 v74, v0
	v_mov_b32_e32 v75, v0
	v_mov_b32_e32 v76, v0
	v_mov_b32_e32 v77, v0
	v_mov_b32_e32 v78, v0
	v_mov_b32_e32 v79, v0
	v_add3_u32 v215, 0, v18, v16
	v_mul_lo_u32 v216, v19, s47
	v_or_b32_e32 v217, v17, v16
	v_mov_b32_e32 v16, v0
	v_mov_b32_e32 v17, v0
	v_mov_b32_e32 v18, v0
	v_mov_b32_e32 v19, v0
	v_mov_b32_e32 v20, v0
	v_mov_b32_e32 v21, v0
	v_mov_b32_e32 v22, v0
	v_mov_b32_e32 v23, v0
	v_mov_b32_e32 v24, v0
	v_mov_b32_e32 v25, v0
	v_mov_b32_e32 v26, v0
	v_mov_b32_e32 v27, v0
	v_mov_b32_e32 v28, v0
	v_mov_b32_e32 v29, v0
	v_mov_b32_e32 v30, v0
	v_mov_b32_e32 v31, v0
	v_mov_b32_e32 v80, v0
	v_mov_b32_e32 v81, v0
	v_mov_b32_e32 v82, v0
	v_mov_b32_e32 v83, v0
	v_mov_b32_e32 v84, v0
	v_mov_b32_e32 v85, v0
	v_mov_b32_e32 v86, v0
	v_mov_b32_e32 v87, v0
	v_mov_b32_e32 v88, v0
	v_mov_b32_e32 v89, v0
	v_mov_b32_e32 v90, v0
	v_mov_b32_e32 v91, v0
	v_mov_b32_e32 v92, v0
	v_mov_b32_e32 v93, v0
	v_mov_b32_e32 v94, v0
	v_mov_b32_e32 v95, v0
	v_mov_b32_e32 v32, v0
	v_mov_b32_e32 v33, v0
	v_mov_b32_e32 v34, v0
	v_mov_b32_e32 v35, v0
	v_mov_b32_e32 v36, v0
	v_mov_b32_e32 v37, v0
	v_mov_b32_e32 v38, v0
	v_mov_b32_e32 v39, v0
	v_mov_b32_e32 v40, v0
	v_mov_b32_e32 v41, v0
	v_mov_b32_e32 v42, v0
	v_mov_b32_e32 v43, v0
	v_mov_b32_e32 v44, v0
	v_mov_b32_e32 v45, v0
	v_mov_b32_e32 v46, v0
	v_mov_b32_e32 v47, v0
	v_mov_b32_e32 v96, v0
	v_mov_b32_e32 v97, v0
	v_mov_b32_e32 v98, v0
	v_mov_b32_e32 v99, v0
	v_mov_b32_e32 v100, v0
	v_mov_b32_e32 v101, v0
	v_mov_b32_e32 v102, v0
	v_mov_b32_e32 v103, v0
	v_mov_b32_e32 v104, v0
	v_mov_b32_e32 v105, v0
	v_mov_b32_e32 v106, v0
	v_mov_b32_e32 v107, v0
	v_mov_b32_e32 v108, v0
	v_mov_b32_e32 v109, v0
	v_mov_b32_e32 v110, v0
	v_mov_b32_e32 v111, v0
	v_mov_b32_e32 v48, v0
	v_mov_b32_e32 v49, v0
	v_mov_b32_e32 v50, v0
	v_mov_b32_e32 v51, v0
	v_mov_b32_e32 v52, v0
	v_mov_b32_e32 v53, v0
	v_mov_b32_e32 v54, v0
	v_mov_b32_e32 v55, v0
	v_mov_b32_e32 v56, v0
	v_mov_b32_e32 v57, v0
	v_mov_b32_e32 v58, v0
	v_mov_b32_e32 v59, v0
	v_mov_b32_e32 v60, v0
	v_mov_b32_e32 v61, v0
	v_mov_b32_e32 v62, v0
	v_mov_b32_e32 v63, v0
	v_mov_b32_e32 v112, v0
	v_mov_b32_e32 v113, v0
	v_mov_b32_e32 v114, v0
	v_mov_b32_e32 v115, v0
	v_mov_b32_e32 v116, v0
	v_mov_b32_e32 v117, v0
	v_mov_b32_e32 v118, v0
	v_mov_b32_e32 v119, v0
	s_waitcnt vmcnt(20)
	v_mov_b32_e32 v120, v0
	v_mov_b32_e32 v121, v0
	v_mov_b32_e32 v122, v0
	v_mov_b32_e32 v123, v0
	s_waitcnt vmcnt(19)
	v_mov_b32_e32 v124, v0
	v_mov_b32_e32 v125, v0
	v_mov_b32_e32 v126, v0
	v_mov_b32_e32 v127, v0
	s_waitcnt vmcnt(7)
	ds_write_b128 v215, v[128:131]
	s_waitcnt vmcnt(6)
	ds_write_b128 v215, v[132:135] offset:36864
	s_waitcnt vmcnt(5)
	ds_write_b128 v215, v[136:139] offset:9216
	s_waitcnt vmcnt(4)
	ds_write_b128 v215, v[140:143] offset:46080
	s_waitcnt vmcnt(3)
	ds_write_b128 v215, v[144:147] offset:18432
	s_waitcnt vmcnt(2)
	ds_write_b128 v215, v[148:151] offset:55296
	s_waitcnt vmcnt(1)
	ds_write_b128 v215, v[152:155] offset:27648
	s_waitcnt vmcnt(0)
	ds_write_b128 v215, v[156:159] offset:64512
	s_lshl_b32 s8, s37, 7
	s_waitcnt vmcnt(1)
	v_add_u32_e32 v152, s8, v214
	s_waitcnt vmcnt(0)
	v_add_u32_e32 v156, s8, v202
	global_load_dwordx4 v[128:131], v152, s[62:63]
	global_load_dwordx4 v[132:135], v156, s[6:7]
	v_add_u32_e32 v136, 0x20000, v152
	v_add_u32_e32 v140, 0x20000, v156
	v_add_u32_e32 v144, 0x40000, v152
	v_add_u32_e32 v148, 0x40000, v156
	v_add_u32_e32 v152, 0x60000, v152
	v_add_u32_e32 v156, 0x60000, v156
	global_load_dwordx4 v[136:139], v136, s[62:63]
	s_add_i32 s37, s37, 1
	global_load_dwordx4 v[140:143], v140, s[6:7]
	s_cmp_lg_u32 s37, 16
	global_load_dwordx4 v[144:147], v144, s[62:63]
	s_mov_b64 s[8:9], -1
	global_load_dwordx4 v[148:151], v148, s[6:7]
	s_nop 0
	global_load_dwordx4 v[152:155], v152, s[62:63]
	s_nop 0
	global_load_dwordx4 v[156:159], v156, s[6:7]
	s_waitcnt lgkmcnt(0)
	s_barrier
	s_branch .LBB1_1301

; template <int EPI, bool RSQ>
; DI void gemm_phase8(const Params& p, int l, const u16* __restrict__ A, int lda, const u16* __restrict__ Bt, int K,
;                    int ntiles_n, int gofs, char* smem, bool latonly = false) {
;     ...
;   auto issue = [&](u32x4 (&qa)[4], u32x4 (&qb)[4]) {
; #pragma unroll
;     for (int i = 0; i < 4; ++i) {
;       qa[i] = *(const u32x4*)((const char*)A + (LAo + i * strideA + (unsigned)Lkt * 128u));
;     ...
;     {
;       const char* As = smem + cur * 73728;
;       const char* Bs = As + 36864;
;       const char* ap = As + (wr * 128 + lr) * 144 + lh * 16;
;       const char* bp = Bs + (wc * 64 + lr) * 144 + lh * 16;
;       bf16x8 fa[3][2], fb[2][2];
;       fa[0][0] = *(const bf16x8*)(ap);
;       fa[0][1] = *(const bf16x8*)(ap + 32 * 144);
;       fb[0][0] = *(const bf16x8*)(bp);
;       fb[0][1] = *(const bf16x8*)(bp + 32 * 144);
;       fa[1][0] = *(const bf16x8*)(ap + 2 * 32 * 144);
;       fa[1][1] = *(const bf16x8*)(ap + 3 * 32 * 144);
;       fb[1][0] = *(const bf16x8*)(bp + 32);
;       fb[1][1] = *(const bf16x8*)(bp + 32 * 144 + 32);
; #pragma unroll
;       for (int u = 0; u < 8; ++u) {
;         const int ks = u >> 1, hf = u & 1, ca = u % 3, cb = ks & 1;
;         if (u + 2 < 8) {
;           const int ks2 = (u + 2) >> 1, hf2 = (u + 2) & 1, cn = (u + 2) % 3;
;           fa[cn][0] = *(const bf16x8*)(ap + (2 * hf2) * 32 * 144 + ks2 * 32);
;           fa[cn][1] = *(const bf16x8*)(ap + (2 * hf2 + 1) * 32 * 144 + ks2 * 32);
;         }
;         __builtin_amdgcn_sched_barrier(0);
;         __builtin_amdgcn_s_setprio(1);
;         acc[2 * hf][0] = MFMA32(fa[ca][0], fb[cb][0], acc[2 * hf][0]);
;         acc[2 * hf][1] = MFMA32(fa[ca][0], fb[cb][1], acc[2 * hf][1]);
;         acc[2 * hf + 1][0] = MFMA32(fa[ca][1], fb[cb][0], acc[2 * hf + 1][0]);
;         acc[2 * hf + 1][1] = MFMA32(fa[ca][1], fb[cb][1], acc[2 * hf + 1][1]);
;         __builtin_amdgcn_s_setprio(0);
;         __builtin_amdgcn_sched_barrier(0);
;         if (u == 0) {
;           if (Lset_valid) issue(La, Lb);
;           __builtin_amdgcn_sched_barrier(0);
;         }
;         if (hf == 1 && ks + 2 < 4) {
;           fb[cb][0] = *(const bf16x8*)(bp + (ks + 2) * 32);
;           fb[cb][1] = *(const bf16x8*)(bp + 32 * 144 + (ks + 2) * 32);
;           __builtin_amdgcn_sched_barrier(0);
;         }
;       }
.LBB1_1301:
	s_mul_i32 s2, s31, 0x12000
	s_add_i32 s2, s2, 0
	v_add_u32_e32 v160, s2, v216
	v_add_u32_e32 v218, v160, v203
	v_add_u32_e32 v160, s2, v213
	v_add_u32_e32 v219, v160, v203
	ds_read_b128 v[176:179], v219 offset:36864
	ds_read_b128 v[160:163], v219 offset:36896
	ds_read_b128 v[188:191], v218 offset:9216
	ds_read_b128 v[180:183], v218 offset:13824
	ds_read_b128 v[184:187], v219 offset:41472
	ds_read_b128 v[164:167], v219 offset:41504
	ds_read_b128 v[220:223], v218
	ds_read_b128 v[172:175], v218 offset:32
	ds_read_b128 v[224:227], v218 offset:4608
	ds_read_b128 v[168:171], v218 offset:4640
	v_subrev_u32_e32 v238, s2, v215
	v_add_u32_e32 v238, 0x12000, v238
	s_setprio 1
	s_waitcnt lgkmcnt(3)
	v_mfma_f32_32x32x16_bf16 v[112:127], v[220:223], v[176:179], v[112:127]
	v_mfma_f32_32x32x16_bf16 v[48:63], v[220:223], v[184:187], v[48:63]
	s_waitcnt lgkmcnt(1)
	v_mfma_f32_32x32x16_bf16 v[96:111], v[224:227], v[176:179], v[96:111]
	v_mfma_f32_32x32x16_bf16 v[32:47], v[224:227], v[184:187], v[32:47]
	s_setprio 0
.LBB1_1308:
	ds_read_b128 v[220:223], v218 offset:9248
	ds_read_b128 v[224:227], v218 offset:13856
	s_setprio 1
	v_mfma_f32_32x32x16_bf16 v[80:95], v[188:191], v[176:179], v[80:95]
	v_mfma_f32_32x32x16_bf16 v[16:31], v[188:191], v[184:187], v[16:31]
	v_mfma_f32_32x32x16_bf16 v[64:79], v[180:183], v[176:179], v[64:79]
	v_mfma_f32_32x32x16_bf16 v[0:15], v[180:183], v[184:187], v[0:15]
	s_setprio 0
	ds_read_b128 v[176:179], v219 offset:36928
	ds_read_b128 v[180:183], v219 offset:41536
	ds_read_b128 v[184:187], v218 offset:64
	ds_read_b128 v[188:191], v218 offset:4672
	s_setprio 1
	v_mfma_f32_32x32x16_bf16 v[112:127], v[172:175], v[160:163], v[112:127]
	v_mfma_f32_32x32x16_bf16 v[48:63], v[172:175], v[164:167], v[48:63]
	s_waitcnt lgkmcnt(6)
	v_mfma_f32_32x32x16_bf16 v[96:111], v[168:171], v[160:163], v[96:111]
	v_mfma_f32_32x32x16_bf16 v[32:47], v[168:171], v[164:167], v[32:47]
	s_setprio 0
	ds_read_b128 v[168:171], v218 offset:9280
	ds_read_b128 v[172:175], v218 offset:13888
	s_setprio 1
	s_waitcnt lgkmcnt(7)
	v_mfma_f32_32x32x16_bf16 v[80:95], v[220:223], v[160:163], v[80:95]
	v_mfma_f32_32x32x16_bf16 v[16:31], v[220:223], v[164:167], v[16:31]
	s_waitcnt lgkmcnt(6)
	v_mfma_f32_32x32x16_bf16 v[64:79], v[224:227], v[160:163], v[64:79]
	v_mfma_f32_32x32x16_bf16 v[0:15], v[224:227], v[164:167], v[0:15]
	s_setprio 0
	ds_read_b128 v[160:163], v219 offset:36960
	ds_read_b128 v[164:167], v219 offset:41568
	ds_read_b128 v[220:223], v218 offset:96
	ds_read_b128 v[224:227], v218 offset:4704
	s_setprio 1
	s_waitcnt lgkmcnt(7)
	v_mfma_f32_32x32x16_bf16 v[112:127], v[184:187], v[176:179], v[112:127]
	v_mfma_f32_32x32x16_bf16 v[48:63], v[184:187], v[180:183], v[48:63]
	s_waitcnt lgkmcnt(6)
	v_mfma_f32_32x32x16_bf16 v[96:111], v[188:191], v[176:179], v[96:111]
	v_mfma_f32_32x32x16_bf16 v[32:47], v[188:191], v[180:183], v[32:47]
	s_setprio 0
	ds_read_b128 v[184:187], v218 offset:9312
	ds_read_b128 v[188:191], v218 offset:13920
	s_waitcnt vmcnt(6)
	ds_write_b128 v238, v[128:131]
	ds_write_b128 v238, v[132:135] offset:36864
	s_setprio 1
	s_waitcnt lgkmcnt(9)
	v_mfma_f32_32x32x16_bf16 v[80:95], v[168:171], v[176:179], v[80:95]
	v_mfma_f32_32x32x16_bf16 v[16:31], v[168:171], v[180:183], v[16:31]
	s_waitcnt lgkmcnt(8)
	v_mfma_f32_32x32x16_bf16 v[64:79], v[172:175], v[176:179], v[64:79]
	v_mfma_f32_32x32x16_bf16 v[0:15], v[172:175], v[180:183], v[0:15]
	s_setprio 0
	s_waitcnt vmcnt(3)
	ds_write_b128 v238, v[136:139] offset:9216
	ds_write_b128 v238, v[140:143] offset:46080
	ds_write_b128 v238, v[144:147] offset:18432
	s_setprio 1
	s_waitcnt lgkmcnt(8)
	v_mfma_f32_32x32x16_bf16 v[112:127], v[220:223], v[160:163], v[112:127]
	v_mfma_f32_32x32x16_bf16 v[48:63], v[220:223], v[164:167], v[48:63]
	s_waitcnt lgkmcnt(7)
	v_mfma_f32_32x32x16_bf16 v[96:111], v[224:227], v[160:163], v[96:111]
	v_mfma_f32_32x32x16_bf16 v[32:47], v[224:227], v[164:167], v[32:47]
	s_setprio 0
	s_waitcnt vmcnt(0)
	ds_write_b128 v238, v[148:151] offset:55296
	ds_write_b128 v238, v[152:155] offset:27648
	ds_write_b128 v238, v[156:159] offset:64512
	s_setprio 1
	s_waitcnt lgkmcnt(9)
	v_mfma_f32_32x32x16_bf16 v[80:95], v[184:187], v[160:163], v[80:95]
	v_mfma_f32_32x32x16_bf16 v[16:31], v[184:187], v[164:167], v[16:31]
	s_waitcnt lgkmcnt(8)
	v_mfma_f32_32x32x16_bf16 v[64:79], v[188:191], v[160:163], v[64:79]
	v_mfma_f32_32x32x16_bf16 v[0:15], v[188:191], v[164:167], v[0:15]
	s_setprio 0
	v_cndmask_b32_e64 v220, 0, 1, s[8:9]
	v_cmp_ne_u32_e64 s[2:3], 1, v220
	s_andn2_b64 vcc, exec, s[8:9]
	s_mov_b64 s[8:9], 0
	s_cbranch_vccnz .Lgemm_issue_done_2
	s_lshl_b32 s8, s37, 7
	s_waitcnt vmcnt(1)
	v_add_u32_e32 v152, s8, v214
	s_waitcnt vmcnt(0)
	v_add_u32_e32 v156, s8, v202
	global_load_dwordx4 v[128:131], v152, s[62:63]
	global_load_dwordx4 v[132:135], v156, s[6:7]
	v_add_u32_e32 v136, 0x20000, v152
	v_add_u32_e32 v140, 0x20000, v156
	v_add_u32_e32 v144, 0x40000, v152
	v_add_u32_e32 v148, 0x40000, v156
	v_add_u32_e32 v152, 0x60000, v152
	v_add_u32_e32 v156, 0x60000, v156
	global_load_dwordx4 v[136:139], v136, s[62:63]
	s_add_i32 s37, s37, 1
	global_load_dwordx4 v[140:143], v140, s[6:7]
	s_cmp_lg_u32 s37, 16
	global_load_dwordx4 v[144:147], v144, s[62:63]
	s_mov_b64 s[8:9], -1
	global_load_dwordx4 v[148:151], v148, s[6:7]
	s_nop 0
	global_load_dwordx4 v[152:155], v152, s[62:63]
	s_nop 0
	global_load_dwordx4 v[156:159], v156, s[6:7]
	s_cbranch_scc1 .Lgemm_issue_done_2
	v_readlane_b32 s8, v236, 44
	s_add_i32 s34, s34, s8
	s_cmp_ge_i32 s34, s21
	s_mov_b64 s[8:9], 0
	s_cbranch_scc1 .LBB1_1307
	s_ashr_i32 s8, s34, 31
	s_lshr_b32 s8, s8, 27
	s_add_i32 s8, s34, s8
	s_ashr_i32 s9, s8, 5
	s_lshl_b32 s9, s9, 3
	s_sub_i32 s10, s20, s9
	s_min_i32 s10, s10, 8
	s_abs_i32 s11, s10
	v_cvt_f32_u32_e32 v202, s11
	s_sub_i32 s14, 0, s11
	s_andn2_b32 s8, s8, 31
	s_sub_i32 s12, s34, s8
	v_rcp_iflag_f32_e32 v202, v202
	s_abs_i32 s8, s12
	s_xor_b32 s13, s12, s10
	s_ashr_i32 s13, s13, 31
	v_mul_f32_e32 v202, 0x4f7ffffe, v202
	v_cvt_u32_f32_e32 v202, v202
	s_nop 0
	v_readfirstlane_b32 s15, v202
	s_mul_i32 s14, s14, s15
	s_mul_hi_u32 s14, s15, s14
	s_add_i32 s15, s15, s14
	s_mul_hi_u32 s14, s8, s15
	s_mul_i32 s15, s14, s11
	s_sub_i32 s8, s8, s15
	s_add_i32 s16, s14, 1
	s_sub_i32 s15, s8, s11
	s_cmp_ge_u32 s8, s11
	s_cselect_b32 s14, s16, s14
	s_cselect_b32 s8, s15, s8
	s_add_i32 s15, s14, 1
	s_cmp_ge_u32 s8, s11
	s_cselect_b32 s8, s15, s14
	s_xor_b32 s8, s8, s13
	s_sub_i32 s8, s8, s13
	s_mul_i32 s10, s8, s10
	s_sub_i32 s10, s12, s10
	s_and_b64 vcc, exec, s[40:41]
	s_add_i32 s9, s10, s9
	s_cbranch_vccnz .LBB1_1306
	s_ashr_i32 s10, s9, 4
	s_mul_i32 s10, s10, 17
	s_and_b32 s9, s9, 15
	s_add_i32 s9, s9, s10
	s_add_i32 s9, s9, 1

; template <int EPI, int MB, int NWC>
; DI void gemm_epi(const Params& p, int l, f32x16 (&acc)[MB][2], const float* rs, int mt, int nt, int gofs,
;                  int wr, int wc, int lr, int lh) {
;     ...
;   } else if (EPI == EPI_RES) {
;     float* Hout = isctx ? p.Hc + ((size_t)bidx * CTXL + tt0) * DM : p.Hl + ((size_t)bidx * SEQ + tt0 - CTXL) * DM;
;     const float* gate = p.mod + ((size_t)l * 17 + (isctx ? 16 : bidx)) * 6144 + gofs;
; #pragma unroll
;     for (int nb = 0; nb < 2; ++nb) {
;       const int col = nt * TN + wc * 64 + nb * 32 + lr;
;       const float gv = gate[col];
; template <int EPI, bool RSQ>
; DI void gemm_phase8(const Params& p, int l, const u16* __restrict__ A, int lda, const u16* __restrict__ Bt, int K,
;                    int ntiles_n, int gofs, char* smem, bool latonly = false) {
;     ...
;     if (last) {
;       if (RSQ) {
; #pragma unroll
;         for (int i = 0; i < 4; ++i) {
;           float v = ssq[i];
;           v += dpp_f<0xB1>(v); v += dpp_f<0x4E>(v); v += dpp_f<0x141>(v);
;           if (sch == 0) rs[srow + 64 * i] = rsqrtf(v / (float)K + 1e-6f);
;           ssq[i] = 0.f;
;         }
;         __syncthreads();
;       }
;       gemm_epi<EPI, 4, 4>(p, l, acc, rs, mt, nt, gofs, wr, wc, lr, lh);
.Lgemm_issue_done_2:
	s_cmp_lg_u32 s36, 15
	s_cselect_b64 s[10:11], -1, 0
	s_and_b64 vcc, exec, s[10:11]
	s_cbranch_vccnz .LBB1_1314
	s_mul_hi_i32 s12, s23, 0x78787879
	s_lshr_b32 s13, s12, 31
	s_ashr_i32 s12, s12, 3
	s_add_i32 s14, s12, s13
	s_mul_i32 s12, s14, 17
	s_sub_i32 s12, s23, s12
	s_lshl_b32 s16, s12, 8
	s_ashr_i32 s15, s14, 31
	v_mov_b32_e32 v160, v200
	v_mov_b32_e32 v161, v201
	v_mov_b32_e32 v162, v194
	s_cmp_gt_i32 s12, 0
	s_mov_b64 s[18:19], -1
	s_cbranch_scc0 .LBB1_1311
	s_lshl_b64 s[12:13], s[14:15], 24
	s_mov_b32 s17, s97
	s_add_u32 s18, s50, s12
	s_addc_u32 s19, s51, s13
	s_lshl_b64 s[12:13], s[16:17], 12
	s_add_u32 s12, s18, s12
	s_addc_u32 s13, s19, s13
	s_add_u32 s12, s12, 0xfff00000
	s_addc_u32 s13, s13, -1
	s_mov_b64 s[18:19], 0

; template <int EPI, bool RSQ>
; DI void gemm_phase8(const Params& p, int l, const u16* __restrict__ A, int lda, const u16* __restrict__ Bt, int K,
;                    int ntiles_n, int gofs, char* smem, bool latonly = false) {
;     ...
;     if (Sset_valid) stash(Sa, Sb, cur ^ 1);
;     __syncthreads();
;     cur ^= 1;
;     if (last) {
;       t += nlb;
;       if (t >= total) return false;
;       decode(t, mt, nt);
;       kt = 0;
;     } else {
;       ++kt;
;     }
;     return true;
.LBB1_1314:
	s_and_b64 vcc, exec, s[2:3]
	s_xor_b32 s31, s31, 1
	s_cbranch_vccnz .LBB1_1316
.LBB1_1316:
	s_mov_b64 s[2:3], -1
	s_and_b64 vcc, exec, s[10:11]
	s_waitcnt lgkmcnt(0)
	s_barrier
	s_cbranch_vccz .LBB1_1318
	s_add_i32 s36, s36, 1
	s_mov_b64 s[2:3], 0

; template <int EPI, bool RSQ>
; DI void gemm_phase8(const Params& p, int l, const u16* __restrict__ A, int lda, const u16* __restrict__ Bt, int K,
;                    int ntiles_n, int gofs, char* smem, bool latonly = false) {
;     ...
;   unsigned LAo = (unsigned)((mt * 256 + srow) * lda + sch * 8) * 2u;
;   unsigned LBo = (unsigned)((nt * 256 + srow) * K + sch * 8) * 2u;
;   const unsigned strideA = (unsigned)(64 * lda) * 2u, strideB = (unsigned)(64 * K) * 2u;
;   auto issue = [&](u32x4 (&qa)[4], u32x4 (&qb)[4]) {
; #pragma unroll
;     for (int i = 0; i < 4; ++i) {
;       qa[i] = *(const u32x4*)((const char*)A + (LAo + i * strideA + (unsigned)Lkt * 128u));
;       qb[i] = *(const u32x4*)((const char*)Bt + (LBo + i * strideB + (unsigned)Lkt * 128u));
;     }
;     if (++Lkt == nk) {
;       Lkt = 0; Lt += nlb;
;       if (Lt < total) {
;         int a, b; decode(Lt, a, b);
;         LAo = (unsigned)((a * 256 + srow) * lda + sch * 8) * 2u;
;         LBo = (unsigned)((b * 256 + srow) * K + sch * 8) * 2u;
;       } else Lvalid = false;
;     }
;   };
;   float ssq[4] = {0.f, 0.f, 0.f, 0.f};
;   auto stash = [&](u32x4 (&qa)[4], u32x4 (&qb)[4], int stage) {
;     char* As = smem + stage * 73728;
;     char* Bs = As + 36864;
; #pragma unroll
;     for (int i = 0; i < 4; ++i) {
;       if (RSQ) { float f[8]; unpack8(qa[i], f);
; #pragma unroll
;         for (int e = 0; e < 8; ++e) ssq[i] = fmaf(f[e], f[e], ssq[i]); }
;       *(u32x4*)(As + (srow + 64 * i) * 144 + sch * 16) = qa[i];
;       *(u32x4*)(Bs + (srow + 64 * i) * 144 + sch * 16) = qb[i];
;     }
;   };
;   auto stash_part = [&](u32x4 (&qa)[4], u32x4 (&qb)[4], int stage, int i) {
;     char* As = smem + stage * 73728;
;     char* Bs = As + 36864;
;     if (RSQ) { float f[8]; unpack8(qa[i], f);
; #pragma unroll
;       for (int e = 0; e < 8; ++e) ssq[i] = fmaf(f[e], f[e], ssq[i]); }
;     *(u32x4*)(As + (srow + 64 * i) * 144 + sch * 16) = qa[i];
;     *(u32x4*)(Bs + (srow + 64 * i) * 144 + sch * 16) = qb[i];
;   };
;   u32x4 ra0[4], rb0[4], ra1[4], rb1[4];
;   f32x16 acc[4][2];
; #pragma unroll
;   for (int a = 0; a < 4; ++a)
; #pragma unroll
;     for (int b = 0; b < 2; ++b)
; #pragma unroll
;       for (int i = 0; i < 16; ++i) acc[a][b][i] = 0.f;
;   issue(ra0, rb0);
;   bool v1 = DEEP && Lvalid;
;   if (v1) issue(ra1, rb1);
;   stash(ra0, rb0, 0);
;   __syncthreads();
.LBB1_1434:
	v_readlane_b32 s0, v235, 59
	v_ashrrev_i32_e32 v1, 3, v0
	v_readlane_b32 s1, v235, 60
	s_add_u32 s0, s0, 0x890000
	v_readlane_b32 s3, v236, 54
	s_addc_u32 s1, s1, 0
	s_add_i32 s15, s2, s3
	v_lshlrev_b32_e32 v31, 11, v1
	v_lshlrev_b32_e32 v2, 4, v0
	v_lshl_add_u32 v3, s15, 19, v31
	v_and_b32_e32 v32, 0x70, v2
	v_lshl_add_u32 v4, s11, 19, v31
	v_or_b32_e32 v203, v3, v32
	v_or_b32_e32 v213, v4, v32
	v_add_u32_e32 v2, 0x20000, v203
	global_load_dwordx4 v[128:131], v203, s[62:63]
	global_load_dwordx4 v[132:135], v213, s[0:1]
	global_load_dwordx4 v[136:139], v2, s[62:63]
	v_add_u32_e32 v2, 0x20000, v213
	global_load_dwordx4 v[140:143], v2, s[0:1]
	v_add_u32_e32 v2, 0x40000, v203
	global_load_dwordx4 v[144:147], v2, s[62:63]
	v_add_u32_e32 v2, 0x40000, v213
	global_load_dwordx4 v[148:151], v2, s[0:1]
	v_add_u32_e32 v2, 0x60000, v203
	global_load_dwordx4 v[152:155], v2, s[62:63]
	v_add_u32_e32 v2, 0x60000, v213
	global_load_dwordx4 v[156:159], v2, s[0:1]
	v_ashrrev_i32_e32 v194, 8, v0
	v_bfe_u32 v2, v0, 6, 2
	v_and_b32_e32 v199, 31, v0
	v_bfe_u32 v200, v0, 5, 1
	v_mov_b32_e32 v0, 0
	v_readlane_b32 s14, v235, 17
	v_mul_lo_u32 v33, v1, s47
	v_lshl_or_b32 v34, v194, 7, v199
	v_lshl_or_b32 v35, v2, 6, v199
	s_mov_b32 s12, 0
	s_mov_b64 s[6:7], -1
	s_mov_b32 s16, 1
	s_mov_b32 s13, s14
	s_mov_b32 s17, 0
	v_lshlrev_b32_e32 v201, 4, v200
	v_lshlrev_b32_e32 v202, 5, v2
	v_mov_b32_e32 v1, v0
	v_mov_b32_e32 v2, v0
	v_mov_b32_e32 v3, v0
	v_mov_b32_e32 v4, v0
	v_mov_b32_e32 v5, v0
	v_mov_b32_e32 v6, v0
	v_mov_b32_e32 v7, v0
	v_mov_b32_e32 v8, v0
	v_mov_b32_e32 v9, v0
	v_mov_b32_e32 v10, v0
	v_mov_b32_e32 v11, v0
	v_mov_b32_e32 v12, v0
	v_mov_b32_e32 v13, v0
	v_mov_b32_e32 v14, v0
	v_mov_b32_e32 v15, v0
	v_mov_b32_e32 v16, v0
	v_mov_b32_e32 v17, v0
	v_mov_b32_e32 v18, v0
	v_mov_b32_e32 v19, v0
	v_mov_b32_e32 v20, v0
	v_mov_b32_e32 v21, v0
	v_mov_b32_e32 v22, v0
	v_mov_b32_e32 v23, v0
	v_mov_b32_e32 v24, v0
	v_mov_b32_e32 v25, v0
	v_mov_b32_e32 v26, v0
	v_mov_b32_e32 v27, v0
	v_mov_b32_e32 v28, v0
	v_mov_b32_e32 v29, v0
	v_mov_b32_e32 v30, v0
	v_add3_u32 v214, 0, v33, v32
	v_mul_lo_u32 v215, v34, s47
	v_mul_u32_u24_e32 v216, 0x90, v35
	v_or_b32_e32 v217, v31, v32
	v_mov_b32_e32 v31, v0
	v_mov_b32_e32 v32, v0
	v_mov_b32_e32 v33, v0
	v_mov_b32_e32 v34, v0
	v_mov_b32_e32 v35, v0
	v_mov_b32_e32 v36, v0
	v_mov_b32_e32 v37, v0
	v_mov_b32_e32 v38, v0
	v_mov_b32_e32 v39, v0
	v_mov_b32_e32 v40, v0
	v_mov_b32_e32 v41, v0
	v_mov_b32_e32 v42, v0
	v_mov_b32_e32 v43, v0
	v_mov_b32_e32 v44, v0
	v_mov_b32_e32 v45, v0
	v_mov_b32_e32 v46, v0
	v_mov_b32_e32 v47, v0
	v_mov_b32_e32 v48, v0
	v_mov_b32_e32 v49, v0
	v_mov_b32_e32 v50, v0
	v_mov_b32_e32 v51, v0
	v_mov_b32_e32 v52, v0
	v_mov_b32_e32 v53, v0
	v_mov_b32_e32 v54, v0
	v_mov_b32_e32 v55, v0
	v_mov_b32_e32 v56, v0
	v_mov_b32_e32 v57, v0
	v_mov_b32_e32 v58, v0
	v_mov_b32_e32 v59, v0
	v_mov_b32_e32 v60, v0
	v_mov_b32_e32 v61, v0
	v_mov_b32_e32 v62, v0
	v_mov_b32_e32 v63, v0
	v_mov_b32_e32 v64, v0
	v_mov_b32_e32 v65, v0
	v_mov_b32_e32 v66, v0
	v_mov_b32_e32 v67, v0
	v_mov_b32_e32 v68, v0
	v_mov_b32_e32 v69, v0
	v_mov_b32_e32 v70, v0
	v_mov_b32_e32 v71, v0
	v_mov_b32_e32 v72, v0
	v_mov_b32_e32 v73, v0
	v_mov_b32_e32 v74, v0
	v_mov_b32_e32 v75, v0
	v_mov_b32_e32 v76, v0
	v_mov_b32_e32 v77, v0
	v_mov_b32_e32 v78, v0
	v_mov_b32_e32 v79, v0
	v_mov_b32_e32 v80, v0
	v_mov_b32_e32 v81, v0
	v_mov_b32_e32 v82, v0
	v_mov_b32_e32 v83, v0
	v_mov_b32_e32 v84, v0
	v_mov_b32_e32 v85, v0
	v_mov_b32_e32 v86, v0
	v_mov_b32_e32 v87, v0
	v_mov_b32_e32 v88, v0
	v_mov_b32_e32 v89, v0
	v_mov_b32_e32 v90, v0
	v_mov_b32_e32 v91, v0
	v_mov_b32_e32 v92, v0
	v_mov_b32_e32 v93, v0
	v_mov_b32_e32 v94, v0
	v_mov_b32_e32 v95, v0
	v_mov_b32_e32 v96, v0
	v_mov_b32_e32 v97, v0
	v_mov_b32_e32 v98, v0
	v_mov_b32_e32 v99, v0
	v_mov_b32_e32 v100, v0
	v_mov_b32_e32 v101, v0
	v_mov_b32_e32 v102, v0
	v_mov_b32_e32 v103, v0
	v_mov_b32_e32 v104, v0
	v_mov_b32_e32 v105, v0
	v_mov_b32_e32 v106, v0
	v_mov_b32_e32 v107, v0
	v_mov_b32_e32 v108, v0
	v_mov_b32_e32 v109, v0
	v_mov_b32_e32 v110, v0
	v_mov_b32_e32 v111, v0
	v_mov_b32_e32 v112, v0
	v_mov_b32_e32 v113, v0
	v_mov_b32_e32 v114, v0
	v_mov_b32_e32 v115, v0
	v_mov_b32_e32 v116, v0
	v_mov_b32_e32 v117, v0
	v_mov_b32_e32 v118, v0
	v_mov_b32_e32 v119, v0
	s_waitcnt vmcnt(20)
	v_mov_b32_e32 v120, v0
	v_mov_b32_e32 v121, v0
	v_mov_b32_e32 v122, v0
	v_mov_b32_e32 v123, v0
	s_waitcnt vmcnt(19)
	v_mov_b32_e32 v124, v0
	v_mov_b32_e32 v125, v0
	v_mov_b32_e32 v126, v0
	v_mov_b32_e32 v127, v0
	s_waitcnt vmcnt(7)
	ds_write_b128 v214, v[128:131]
	s_waitcnt vmcnt(6)
	ds_write_b128 v214, v[132:135] offset:36864
	s_waitcnt vmcnt(5)
	ds_write_b128 v214, v[136:139] offset:9216
	s_waitcnt vmcnt(4)
	ds_write_b128 v214, v[140:143] offset:46080
	s_waitcnt vmcnt(3)
	ds_write_b128 v214, v[144:147] offset:18432
	s_waitcnt vmcnt(2)
	ds_write_b128 v214, v[148:151] offset:55296
	s_waitcnt vmcnt(1)
	ds_write_b128 v214, v[152:155] offset:27648
	s_waitcnt vmcnt(0)
	ds_write_b128 v214, v[156:159] offset:64512
	s_lshl_b32 s6, s16, 7
	s_waitcnt vmcnt(1)
	v_add_u32_e32 v152, s6, v203
	s_waitcnt vmcnt(0)
	v_add_u32_e32 v156, s6, v213
	global_load_dwordx4 v[128:131], v152, s[62:63]
	global_load_dwordx4 v[132:135], v156, s[0:1]
	v_add_u32_e32 v136, 0x20000, v152
	v_add_u32_e32 v140, 0x20000, v156
	v_add_u32_e32 v144, 0x40000, v152
	v_add_u32_e32 v148, 0x40000, v156
	v_add_u32_e32 v152, 0x60000, v152
	v_add_u32_e32 v156, 0x60000, v156
	global_load_dwordx4 v[136:139], v136, s[62:63]
	s_add_i32 s16, s16, 1
	global_load_dwordx4 v[140:143], v140, s[0:1]
	s_cmp_lg_u32 s16, 16
	global_load_dwordx4 v[144:147], v144, s[62:63]
	s_mov_b64 s[6:7], -1
	global_load_dwordx4 v[148:151], v148, s[0:1]
	s_nop 0
	global_load_dwordx4 v[152:155], v152, s[62:63]
	s_nop 0
	global_load_dwordx4 v[156:159], v156, s[0:1]
	s_waitcnt lgkmcnt(0)
	s_barrier
	s_branch .LBB1_1437

; template <int EPI, bool RSQ>
; DI void gemm_phase8(const Params& p, int l, const u16* __restrict__ A, int lda, const u16* __restrict__ Bt, int K,
;                    int ntiles_n, int gofs, char* smem, bool latonly = false) {
;     ...
;   auto issue = [&](u32x4 (&qa)[4], u32x4 (&qb)[4]) {
; #pragma unroll
;     for (int i = 0; i < 4; ++i) {
;       qa[i] = *(const u32x4*)((const char*)A + (LAo + i * strideA + (unsigned)Lkt * 128u));
;     ...
;     {
;       const char* As = smem + cur * 73728;
;       const char* Bs = As + 36864;
;       const char* ap = As + (wr * 128 + lr) * 144 + lh * 16;
;       const char* bp = Bs + (wc * 64 + lr) * 144 + lh * 16;
;       bf16x8 fa[3][2], fb[2][2];
;       fa[0][0] = *(const bf16x8*)(ap);
;       fa[0][1] = *(const bf16x8*)(ap + 32 * 144);
;       fb[0][0] = *(const bf16x8*)(bp);
;       fb[0][1] = *(const bf16x8*)(bp + 32 * 144);
;       fa[1][0] = *(const bf16x8*)(ap + 2 * 32 * 144);
;       fa[1][1] = *(const bf16x8*)(ap + 3 * 32 * 144);
;       fb[1][0] = *(const bf16x8*)(bp + 32);
;       fb[1][1] = *(const bf16x8*)(bp + 32 * 144 + 32);
; #pragma unroll
;       for (int u = 0; u < 8; ++u) {
;         const int ks = u >> 1, hf = u & 1, ca = u % 3, cb = ks & 1;
;         if (u + 2 < 8) {
;           const int ks2 = (u + 2) >> 1, hf2 = (u + 2) & 1, cn = (u + 2) % 3;
;           fa[cn][0] = *(const bf16x8*)(ap + (2 * hf2) * 32 * 144 + ks2 * 32);
;           fa[cn][1] = *(const bf16x8*)(ap + (2 * hf2 + 1) * 32 * 144 + ks2 * 32);
;         }
;         __builtin_amdgcn_sched_barrier(0);
;         __builtin_amdgcn_s_setprio(1);
;         acc[2 * hf][0] = MFMA32(fa[ca][0], fb[cb][0], acc[2 * hf][0]);
;         acc[2 * hf][1] = MFMA32(fa[ca][0], fb[cb][1], acc[2 * hf][1]);
;         acc[2 * hf + 1][0] = MFMA32(fa[ca][1], fb[cb][0], acc[2 * hf + 1][0]);
;         acc[2 * hf + 1][1] = MFMA32(fa[ca][1], fb[cb][1], acc[2 * hf + 1][1]);
;         __builtin_amdgcn_s_setprio(0);
;         __builtin_amdgcn_sched_barrier(0);
;         if (u == 0) {
;           if (Lset_valid) issue(La, Lb);
;           __builtin_amdgcn_sched_barrier(0);
;         }
;         if (hf == 1 && ks + 2 < 4) {
;           fb[cb][0] = *(const bf16x8*)(bp + (ks + 2) * 32);
;           fb[cb][1] = *(const bf16x8*)(bp + 32 * 144 + (ks + 2) * 32);
;           __builtin_amdgcn_sched_barrier(0);
;         }
;       }
.LBB1_1437:
	s_mul_i32 s2, s12, 0x12000
	s_add_i32 s2, s2, 0
	v_add_u32_e32 v160, s2, v215
	v_add_u32_e32 v218, v160, v201
	v_add_u32_e32 v160, s2, v216
	v_add_u32_e32 v219, v160, v201
	ds_read_b128 v[176:179], v219 offset:36864
	ds_read_b128 v[160:163], v219 offset:36896
	ds_read_b128 v[188:191], v218 offset:9216
	ds_read_b128 v[180:183], v218 offset:13824
	ds_read_b128 v[184:187], v219 offset:41472
	ds_read_b128 v[164:167], v219 offset:41504
	ds_read_b128 v[220:223], v218
	ds_read_b128 v[172:175], v218 offset:32
	ds_read_b128 v[224:227], v218 offset:4608
	ds_read_b128 v[168:171], v218 offset:4640
	v_subrev_u32_e32 v238, s2, v214
	v_add_u32_e32 v238, 0x12000, v238
	s_setprio 1
	s_waitcnt lgkmcnt(3)
	v_mfma_f32_32x32x16_bf16 v[112:127], v[220:223], v[176:179], v[112:127]
	v_mfma_f32_32x32x16_bf16 v[96:111], v[220:223], v[184:187], v[96:111]
	s_waitcnt lgkmcnt(1)
	v_mfma_f32_32x32x16_bf16 v[80:95], v[224:227], v[176:179], v[80:95]
	v_mfma_f32_32x32x16_bf16 v[64:79], v[224:227], v[184:187], v[64:79]
	s_setprio 0
.LBB1_1444:
	ds_read_b128 v[220:223], v218 offset:9248
	ds_read_b128 v[224:227], v218 offset:13856
	s_setprio 1
	v_mfma_f32_32x32x16_bf16 v[48:63], v[188:191], v[176:179], v[48:63]
	v_mfma_f32_32x32x16_bf16 v[32:47], v[188:191], v[184:187], v[32:47]
	v_mfma_f32_32x32x16_bf16 v[16:31], v[180:183], v[176:179], v[16:31]
	v_mfma_f32_32x32x16_bf16 v[0:15], v[180:183], v[184:187], v[0:15]
	s_setprio 0
	ds_read_b128 v[176:179], v219 offset:36928
	ds_read_b128 v[180:183], v219 offset:41536
	ds_read_b128 v[184:187], v218 offset:64
	ds_read_b128 v[188:191], v218 offset:4672
	s_setprio 1
	v_mfma_f32_32x32x16_bf16 v[112:127], v[172:175], v[160:163], v[112:127]
	v_mfma_f32_32x32x16_bf16 v[96:111], v[172:175], v[164:167], v[96:111]
	s_waitcnt lgkmcnt(6)
	v_mfma_f32_32x32x16_bf16 v[80:95], v[168:171], v[160:163], v[80:95]
	v_mfma_f32_32x32x16_bf16 v[64:79], v[168:171], v[164:167], v[64:79]
	s_setprio 0
	ds_read_b128 v[168:171], v218 offset:9280
	ds_read_b128 v[172:175], v218 offset:13888
	s_setprio 1
	s_waitcnt lgkmcnt(7)
	v_mfma_f32_32x32x16_bf16 v[48:63], v[220:223], v[160:163], v[48:63]
	v_mfma_f32_32x32x16_bf16 v[32:47], v[220:223], v[164:167], v[32:47]
	s_waitcnt lgkmcnt(6)
	v_mfma_f32_32x32x16_bf16 v[16:31], v[224:227], v[160:163], v[16:31]
	v_mfma_f32_32x32x16_bf16 v[0:15], v[224:227], v[164:167], v[0:15]
	s_setprio 0
	ds_read_b128 v[160:163], v219 offset:36960
	ds_read_b128 v[164:167], v219 offset:41568
	ds_read_b128 v[220:223], v218 offset:96
	ds_read_b128 v[224:227], v218 offset:4704
	s_setprio 1
	s_waitcnt lgkmcnt(7)
	v_mfma_f32_32x32x16_bf16 v[112:127], v[184:187], v[176:179], v[112:127]
	v_mfma_f32_32x32x16_bf16 v[96:111], v[184:187], v[180:183], v[96:111]
	s_waitcnt lgkmcnt(6)
	v_mfma_f32_32x32x16_bf16 v[80:95], v[188:191], v[176:179], v[80:95]
	v_mfma_f32_32x32x16_bf16 v[64:79], v[188:191], v[180:183], v[64:79]
	s_setprio 0
	ds_read_b128 v[184:187], v218 offset:9312
	ds_read_b128 v[188:191], v218 offset:13920
	s_waitcnt vmcnt(6)
	ds_write_b128 v238, v[128:131]
	ds_write_b128 v238, v[132:135] offset:36864
	s_setprio 1
	s_waitcnt lgkmcnt(9)
	v_mfma_f32_32x32x16_bf16 v[48:63], v[168:171], v[176:179], v[48:63]
	v_mfma_f32_32x32x16_bf16 v[32:47], v[168:171], v[180:183], v[32:47]
	s_waitcnt lgkmcnt(8)
	v_mfma_f32_32x32x16_bf16 v[16:31], v[172:175], v[176:179], v[16:31]
	v_mfma_f32_32x32x16_bf16 v[0:15], v[172:175], v[180:183], v[0:15]
	s_setprio 0
	s_waitcnt vmcnt(3)
	ds_write_b128 v238, v[136:139] offset:9216
	ds_write_b128 v238, v[140:143] offset:46080
	ds_write_b128 v238, v[144:147] offset:18432
	s_setprio 1
	s_waitcnt lgkmcnt(8)
	v_mfma_f32_32x32x16_bf16 v[112:127], v[220:223], v[160:163], v[112:127]
	v_mfma_f32_32x32x16_bf16 v[96:111], v[220:223], v[164:167], v[96:111]
	s_waitcnt lgkmcnt(7)
	v_mfma_f32_32x32x16_bf16 v[80:95], v[224:227], v[160:163], v[80:95]
	v_mfma_f32_32x32x16_bf16 v[64:79], v[224:227], v[164:167], v[64:79]
	s_setprio 0
	s_waitcnt vmcnt(0)
	ds_write_b128 v238, v[148:151] offset:55296
	ds_write_b128 v238, v[152:155] offset:27648
	ds_write_b128 v238, v[156:159] offset:64512
	s_setprio 1
	s_waitcnt lgkmcnt(9)
	v_mfma_f32_32x32x16_bf16 v[48:63], v[184:187], v[160:163], v[48:63]
	v_mfma_f32_32x32x16_bf16 v[32:47], v[184:187], v[164:167], v[32:47]
	s_waitcnt lgkmcnt(8)
	v_mfma_f32_32x32x16_bf16 v[16:31], v[188:191], v[160:163], v[16:31]
	v_mfma_f32_32x32x16_bf16 v[0:15], v[188:191], v[164:167], v[0:15]
	s_setprio 0
	v_cndmask_b32_e64 v220, 0, 1, s[6:7]
	v_cmp_ne_u32_e64 s[2:3], 1, v220
	s_andn2_b64 vcc, exec, s[6:7]
	s_mov_b64 s[6:7], 0
	s_cbranch_vccnz .Lgemm_issue_done_3
	s_lshl_b32 s6, s16, 7
	s_waitcnt vmcnt(1)
	v_add_u32_e32 v152, s6, v203
	s_waitcnt vmcnt(0)
	v_add_u32_e32 v156, s6, v213
	global_load_dwordx4 v[128:131], v152, s[62:63]
	global_load_dwordx4 v[132:135], v156, s[0:1]
	v_add_u32_e32 v136, 0x20000, v152
	v_add_u32_e32 v140, 0x20000, v156
	v_add_u32_e32 v144, 0x40000, v152
	v_add_u32_e32 v148, 0x40000, v156
	v_add_u32_e32 v152, 0x60000, v152
	v_add_u32_e32 v156, 0x60000, v156
	global_load_dwordx4 v[136:139], v136, s[62:63]
	s_add_i32 s16, s16, 1
	global_load_dwordx4 v[140:143], v140, s[0:1]
	s_cmp_lg_u32 s16, 16
	global_load_dwordx4 v[144:147], v144, s[62:63]
	s_mov_b64 s[6:7], -1
	global_load_dwordx4 v[148:151], v148, s[0:1]
	s_nop 0
	global_load_dwordx4 v[152:155], v152, s[62:63]
	s_nop 0
	global_load_dwordx4 v[156:159], v156, s[0:1]
	s_cbranch_scc1 .Lgemm_issue_done_3
	v_readlane_b32 s6, v236, 44
	s_add_i32 s13, s13, s6
	s_cmp_ge_i32 s13, s10
	s_mov_b64 s[6:7], 0
	s_cbranch_scc1 .LBB1_1443
	s_mul_hi_i32 s6, s13, 0x2e8ba2e9
	s_lshr_b32 s7, s6, 31
	s_ashr_i32 s6, s6, 5
	s_add_i32 s6, s6, s7
	s_lshl_b32 s7, s6, 3
	s_sub_i32 s8, s20, s7
	s_min_i32 s8, s8, 8
	s_abs_i32 s9, s8
	v_cvt_f32_u32_e32 v203, s9
	s_sub_i32 s19, 0, s9
	s_mulk_i32 s6, 0xff50
	s_add_i32 s16, s6, s13
	v_rcp_iflag_f32_e32 v203, v203
	s_abs_i32 s6, s16
	s_xor_b32 s18, s16, s8
	s_ashr_i32 s18, s18, 31
	v_mul_f32_e32 v203, 0x4f7ffffe, v203
	v_cvt_u32_f32_e32 v203, v203
	s_nop 0
	v_readfirstlane_b32 s22, v203
	s_mul_i32 s19, s19, s22
	s_mul_hi_u32 s19, s22, s19
	s_add_i32 s22, s22, s19
	s_mul_hi_u32 s19, s6, s22
	s_mul_i32 s22, s19, s9
	s_sub_i32 s6, s6, s22
	s_add_i32 s23, s19, 1
	s_sub_i32 s22, s6, s9
	s_cmp_ge_u32 s6, s9
	s_cselect_b32 s19, s23, s19
	s_cselect_b32 s6, s22, s6
	s_add_i32 s22, s19, 1
	s_cmp_ge_u32 s6, s9
	s_cselect_b32 s6, s22, s19
	s_xor_b32 s6, s6, s18
	s_sub_i32 s6, s6, s18
	s_mul_i32 s8, s6, s8
	s_sub_i32 s8, s16, s8
	s_and_b64 vcc, exec, s[40:41]
	s_add_i32 s7, s8, s7
	s_cbranch_vccnz .LBB1_1442
	s_ashr_i32 s8, s7, 4
	s_mul_i32 s8, s8, 17
	s_and_b32 s7, s7, 15
	s_add_i32 s7, s7, s8
	s_add_i32 s7, s7, 1

; DI u16 f2bf(float a) { return (u16)(pack2(a, 0.f) & 0xffffu); }
; DI float siluf(float x) { return x * __builtin_amdgcn_rcpf(1.f + __expf(-x)); }
; DI int crow(int i, int h) { return (i & 3) + 8 * (i >> 2) + 4 * h; }
; template <int EPI, int MB, int NWC>
; DI void gemm_epi(const Params& p, int l, f32x16 (&acc)[MB][2], const float* rs, int mt, int nt, int gofs,
;                  int wr, int wc, int lr, int lh) {
;     ...
; #pragma unroll
;     for (int mb = 0; mb < MB; ++mb)
; #pragma unroll
;       for (int i = 0; i < 16; ++i) {
;         const int row = mt * TM + wr * WRS + mb * 32 + crow(i, lh);
;         const float a = acc[mb][0][i], b = acc[mb][1][i];
;         *(u16*)((char*)p.P + (unsigned)((row * FFH + (nt * NWC + wc) * 32 + lr) * 2)) = f2bf(siluf(a) * b);
;       }
; template <int EPI, bool RSQ>
; DI void gemm_phase8(const Params& p, int l, const u16* __restrict__ A, int lda, const u16* __restrict__ Bt, int K,
;                    int ntiles_n, int gofs, char* smem, bool latonly = false) {
;     ...
;     if (last) {
;       if (RSQ) {
; #pragma unroll
;         for (int i = 0; i < 4; ++i) {
;           float v = ssq[i];
;           v += dpp_f<0xB1>(v); v += dpp_f<0x4E>(v); v += dpp_f<0x141>(v);
;           if (sch == 0) rs[srow + 64 * i] = rsqrtf(v / (float)K + 1e-6f);
;           ssq[i] = 0.f;
;         }
;         __syncthreads();
;       }
;       gemm_epi<EPI, 4, 4>(p, l, acc, rs, mt, nt, gofs, wr, wc, lr, lh);
.Lgemm_issue_done_3:
	s_cmp_lg_u32 s17, 15
	s_cselect_b64 s[8:9], -1, 0
	s_and_b64 vcc, exec, s[8:9]
	s_cbranch_vccnz .LBB1_1446
	v_mul_f32_e32 v162, 0xbfb8aa3b, v112
	v_exp_f32_e32 v162, v162
	v_mov_b32_e32 v160, v199
	v_mov_b32_e32 v161, v200
	v_mov_b32_e32 v163, v194
	v_add_f32_e32 v162, 1.0, v162
	v_rcp_f32_e32 v162, v162
	s_mov_b32 s19, 0x58000
	v_mul_f32_e32 v112, v112, v162
	v_mul_f32_e32 v96, v96, v112
	v_mul_f32_e32 v112, 0xbfb8aa3b, v113
	v_exp_f32_e32 v112, v112
	s_mul_i32 s18, s15, 0xb0000
	v_mul_lo_u32 v163, v163, s19
	s_movk_i32 s19, 0x2c00
	v_add_f32_e32 v112, 1.0, v112
	v_rcp_f32_e32 v112, v112
	v_cvt_pk_bf16_f32 v162, v96, s0
	v_lshl_or_b32 v96, s11, 7, v202
	v_mul_lo_u32 v161, v161, s19
	v_mul_f32_e32 v112, v113, v112
	v_mul_f32_e32 v113, 0xbfb8aa3b, v114
	v_exp_f32_e32 v113, v113
	v_add_u32_e32 v96, s18, v96
	v_add3_u32 v96, v96, v160, v161
	v_mul_f32_e32 v160, 0xbfb8aa3b, v115
	v_add_f32_e32 v113, 1.0, v113
	v_rcp_f32_e32 v113, v113
	v_exp_f32_e32 v160, v160
	v_add_lshl_u32 v96, v96, v163, 1
	v_mul_f32_e32 v97, v97, v112
	v_cvt_pk_bf16_f32 v97, v97, s0
	v_add_u32_e32 v112, 0x1600, v96
	global_store_short v112, v97, s[64:65]
	v_mul_f32_e32 v97, v114, v113
	v_mul_f32_e32 v97, v98, v97
	v_add_f32_e32 v98, 1.0, v160
	v_rcp_f32_e32 v98, v98
	v_cvt_pk_bf16_f32 v97, v97, s0
	v_add_u32_e32 v112, 0x2c00, v96
	global_store_short v112, v97, s[64:65]
	v_mul_f32_e32 v97, v115, v98
	v_mul_f32_e32 v98, 0xbfb8aa3b, v116
	v_exp_f32_e32 v98, v98
	v_mul_f32_e32 v112, 0xbfb8aa3b, v117
	v_exp_f32_e32 v112, v112
	v_mul_f32_e32 v97, v99, v97
	v_add_f32_e32 v98, 1.0, v98
	v_rcp_f32_e32 v98, v98
	v_cvt_pk_bf16_f32 v97, v97, s0
	v_add_u32_e32 v99, 0x4200, v96
	global_store_short v99, v97, s[64:65]
	v_mul_f32_e32 v97, v116, v98
	v_add_f32_e32 v98, 1.0, v112
	v_rcp_f32_e32 v98, v98
	v_mul_f32_e32 v97, v100, v97
	v_cvt_pk_bf16_f32 v97, v97, s0
	v_add_u32_e32 v99, 0xb000, v96
	global_store_short v99, v97, s[64:65]
	v_mul_f32_e32 v97, v117, v98
	v_mul_f32_e32 v98, 0xbfb8aa3b, v118
	v_exp_f32_e32 v98, v98
	v_mul_f32_e32 v100, 0xbfb8aa3b, v119
	v_exp_f32_e32 v100, v100
	v_mul_f32_e32 v97, v101, v97
	v_add_f32_e32 v98, 1.0, v98
	v_rcp_f32_e32 v98, v98
	v_cvt_pk_bf16_f32 v97, v97, s0
	v_add_u32_e32 v99, 0xc600, v96
	global_store_short v99, v97, s[64:65]
	v_mul_f32_e32 v97, v118, v98
	v_add_f32_e32 v98, 1.0, v100
	v_rcp_f32_e32 v98, v98
	v_mul_f32_e32 v97, v102, v97
	v_cvt_pk_bf16_f32 v97, v97, s0
	v_add_u32_e32 v99, 0xdc00, v96
	global_store_short v99, v97, s[64:65]
	v_mul_f32_e32 v97, v119, v98
	v_mul_f32_e32 v98, 0xbfb8aa3b, v120
	v_exp_f32_e32 v98, v98
	v_mul_f32_e32 v100, 0xbfb8aa3b, v121
	v_exp_f32_e32 v100, v100
	v_mul_f32_e32 v97, v103, v97
	v_add_f32_e32 v98, 1.0, v98
	v_rcp_f32_e32 v98, v98
	v_cvt_pk_bf16_f32 v97, v97, s0
	v_add_u32_e32 v99, 0xf200, v96
	global_store_short v99, v97, s[64:65]
	v_mul_f32_e32 v97, v120, v98
	v_add_f32_e32 v98, 1.0, v100
	v_rcp_f32_e32 v98, v98
	v_mul_f32_e32 v97, v104, v97
	v_cvt_pk_bf16_f32 v97, v97, s0
	v_add_u32_e32 v99, 0x16000, v96
	global_store_short v99, v97, s[64:65]
	v_mul_f32_e32 v97, v121, v98
	v_mul_f32_e32 v98, 0xbfb8aa3b, v122
	v_exp_f32_e32 v98, v98
	v_mul_f32_e32 v100, 0xbfb8aa3b, v123
	v_exp_f32_e32 v100, v100
	v_mul_f32_e32 v97, v105, v97
	v_add_f32_e32 v98, 1.0, v98
	v_rcp_f32_e32 v98, v98
	v_cvt_pk_bf16_f32 v97, v97, s0
	v_add_u32_e32 v99, 0x17600, v96
	global_store_short v99, v97, s[64:65]
	v_mul_f32_e32 v97, v122, v98
	v_add_f32_e32 v98, 1.0, v100
	v_rcp_f32_e32 v98, v98
	v_mul_f32_e32 v97, v106, v97
	v_cvt_pk_bf16_f32 v97, v97, s0
	v_add_u32_e32 v99, 0x18c00, v96
	global_store_short v99, v97, s[64:65]
	v_mul_f32_e32 v97, v123, v98
	v_mul_f32_e32 v98, 0xbfb8aa3b, v124
	v_exp_f32_e32 v98, v98
	v_mul_f32_e32 v100, 0xbfb8aa3b, v125
	v_exp_f32_e32 v100, v100
	v_mul_f32_e32 v97, v107, v97
	v_add_f32_e32 v98, 1.0, v98
	v_rcp_f32_e32 v98, v98
	v_cvt_pk_bf16_f32 v97, v97, s0
	v_add_u32_e32 v99, 0x1a200, v96
	global_store_short v99, v97, s[64:65]
	v_mul_f32_e32 v97, v124, v98
	v_add_f32_e32 v98, 1.0, v100
	v_rcp_f32_e32 v98, v98
	v_mul_f32_e32 v97, v108, v97
	v_cvt_pk_bf16_f32 v97, v97, s0
	v_add_u32_e32 v99, 0x21000, v96
	global_store_short v99, v97, s[64:65]
	v_mul_f32_e32 v97, v125, v98
	v_mul_f32_e32 v98, 0xbfb8aa3b, v126
	v_exp_f32_e32 v98, v98
	v_mul_f32_e32 v100, 0xbfb8aa3b, v127
	v_exp_f32_e32 v100, v100
	v_mul_f32_e32 v97, v109, v97
	v_add_f32_e32 v98, 1.0, v98
	v_rcp_f32_e32 v98, v98
	v_cvt_pk_bf16_f32 v97, v97, s0
	v_add_u32_e32 v99, 0x22600, v96
	global_store_short v99, v97, s[64:65]
	v_mul_f32_e32 v97, v126, v98
	v_add_f32_e32 v98, 1.0, v100
	v_rcp_f32_e32 v98, v98
	v_mul_f32_e32 v97, v110, v97
	v_cvt_pk_bf16_f32 v97, v97, s0
	v_add_u32_e32 v99, 0x23c00, v96
	global_store_short v99, v97, s[64:65]
	v_mul_f32_e32 v97, v127, v98
	v_mul_f32_e32 v98, 0xbfb8aa3b, v80
	v_exp_f32_e32 v98, v98
	v_mul_f32_e32 v100, 0xbfb8aa3b, v81
	v_exp_f32_e32 v100, v100
	v_mul_f32_e32 v97, v111, v97
	v_add_f32_e32 v98, 1.0, v98
	v_rcp_f32_e32 v98, v98
	v_cvt_pk_bf16_f32 v97, v97, s0
	v_add_u32_e32 v99, 0x25200, v96
	global_store_short v99, v97, s[64:65]
	v_mul_f32_e32 v80, v80, v98
	v_mul_f32_e32 v64, v64, v80
	v_add_f32_e32 v80, 1.0, v100
	v_rcp_f32_e32 v80, v80
	v_cvt_pk_bf16_f32 v64, v64, s0
	v_add_u32_e32 v97, 0x2c000, v96
	global_store_short v97, v64, s[64:65]
	v_mul_f32_e32 v64, v81, v80
	v_mul_f32_e32 v80, 0xbfb8aa3b, v82
	v_exp_f32_e32 v80, v80
	v_mul_f32_e32 v81, 0xbfb8aa3b, v83
	v_exp_f32_e32 v81, v81
	v_mul_f32_e32 v64, v65, v64
	v_add_f32_e32 v80, 1.0, v80
	v_rcp_f32_e32 v80, v80
	v_cvt_pk_bf16_f32 v64, v64, s0
	v_add_u32_e32 v65, 0x2d600, v96
	global_store_short v65, v64, s[64:65]
; DI u16 f2bf(float a) { return (u16)(pack2(a, 0.f) & 0xffffu); }
; DI float siluf(float x) { return x * __builtin_amdgcn_rcpf(1.f + __expf(-x)); }
; DI int crow(int i, int h) { return (i & 3) + 8 * (i >> 2) + 4 * h; }
; template <int EPI, int MB, int NWC>
; DI void gemm_epi(const Params& p, int l, f32x16 (&acc)[MB][2], const float* rs, int mt, int nt, int gofs,
;                  int wr, int wc, int lr, int lh) {
;     ...
; #pragma unroll
;     for (int mb = 0; mb < MB; ++mb)
; #pragma unroll
;       for (int i = 0; i < 16; ++i) {
;         const int row = mt * TM + wr * WRS + mb * 32 + crow(i, lh);
;         const float a = acc[mb][0][i], b = acc[mb][1][i];
;         *(u16*)((char*)p.P + (unsigned)((row * FFH + (nt * NWC + wc) * 32 + lr) * 2)) = f2bf(siluf(a) * b);
;       }
	v_add_f32_e32 v65, 1.0, v81
	v_rcp_f32_e32 v65, v65
	v_mul_f32_e32 v64, v82, v80
	v_mul_f32_e32 v64, v66, v64
	v_cvt_pk_bf16_f32 v64, v64, s0
	v_add_u32_e32 v66, 0x2ec00, v96
	global_store_short v66, v64, s[64:65]
	v_mul_f32_e32 v64, v83, v65
	v_mul_f32_e32 v65, 0xbfb8aa3b, v84
	v_exp_f32_e32 v65, v65
	v_mul_f32_e32 v64, v67, v64
	v_mul_f32_e32 v67, 0xbfb8aa3b, v85
	v_exp_f32_e32 v67, v67
	v_add_f32_e32 v65, 1.0, v65
	v_rcp_f32_e32 v65, v65
	v_cvt_pk_bf16_f32 v64, v64, s0
	v_add_u32_e32 v66, 0x30200, v96
	global_store_short v66, v64, s[64:65]
	v_mul_f32_e32 v64, v84, v65
	v_add_f32_e32 v65, 1.0, v67
	v_rcp_f32_e32 v65, v65
	v_mul_f32_e32 v64, v68, v64
	v_cvt_pk_bf16_f32 v64, v64, s0
	v_add_u32_e32 v66, 0x37000, v96
	global_store_short v66, v64, s[64:65]
	v_mul_f32_e32 v64, v85, v65
	v_mul_f32_e32 v65, 0xbfb8aa3b, v86
	v_exp_f32_e32 v65, v65
	v_mul_f32_e32 v67, 0xbfb8aa3b, v87
	v_exp_f32_e32 v67, v67
	v_mul_f32_e32 v64, v69, v64
	v_add_f32_e32 v65, 1.0, v65
	v_rcp_f32_e32 v65, v65
	v_cvt_pk_bf16_f32 v64, v64, s0
	v_add_u32_e32 v66, 0x38600, v96
	global_store_short v66, v64, s[64:65]
	v_mul_f32_e32 v64, v86, v65
	v_add_f32_e32 v65, 1.0, v67
	v_rcp_f32_e32 v65, v65
	v_mul_f32_e32 v64, v70, v64
	v_cvt_pk_bf16_f32 v64, v64, s0
	v_add_u32_e32 v66, 0x39c00, v96
	global_store_short v66, v64, s[64:65]
	v_mul_f32_e32 v64, v87, v65
	v_mul_f32_e32 v65, 0xbfb8aa3b, v88
	v_exp_f32_e32 v65, v65
	v_mul_f32_e32 v67, 0xbfb8aa3b, v89
	v_exp_f32_e32 v67, v67
	v_mul_f32_e32 v64, v71, v64
	v_add_f32_e32 v65, 1.0, v65
	v_rcp_f32_e32 v65, v65
	v_cvt_pk_bf16_f32 v64, v64, s0
	v_add_u32_e32 v66, 0x3b200, v96
	global_store_short v66, v64, s[64:65]
	v_mul_f32_e32 v64, v88, v65
	v_add_f32_e32 v65, 1.0, v67
	v_rcp_f32_e32 v65, v65
	v_mul_f32_e32 v64, v72, v64
	v_cvt_pk_bf16_f32 v64, v64, s0
	v_add_u32_e32 v66, 0x42000, v96
	global_store_short v66, v64, s[64:65]
	v_mul_f32_e32 v64, v89, v65
	v_mul_f32_e32 v65, 0xbfb8aa3b, v90
	v_exp_f32_e32 v65, v65
	v_mul_f32_e32 v67, 0xbfb8aa3b, v91
	v_exp_f32_e32 v67, v67
	v_mul_f32_e32 v64, v73, v64
	v_add_f32_e32 v65, 1.0, v65
	v_rcp_f32_e32 v65, v65
	v_cvt_pk_bf16_f32 v64, v64, s0
	v_add_u32_e32 v66, 0x43600, v96
	global_store_short v66, v64, s[64:65]
	v_mul_f32_e32 v64, v90, v65
	v_add_f32_e32 v65, 1.0, v67
	v_rcp_f32_e32 v65, v65
	v_mul_f32_e32 v64, v74, v64
	v_cvt_pk_bf16_f32 v64, v64, s0
	v_add_u32_e32 v66, 0x44c00, v96
	global_store_short v66, v64, s[64:65]
	v_mul_f32_e32 v64, v91, v65
	v_mul_f32_e32 v65, 0xbfb8aa3b, v92
	v_exp_f32_e32 v65, v65
	v_mul_f32_e32 v67, 0xbfb8aa3b, v93
	v_exp_f32_e32 v67, v67
	v_mul_f32_e32 v64, v75, v64
	v_add_f32_e32 v65, 1.0, v65
	v_rcp_f32_e32 v65, v65
	v_cvt_pk_bf16_f32 v64, v64, s0
	v_add_u32_e32 v66, 0x46200, v96
	global_store_short v66, v64, s[64:65]
	v_mul_f32_e32 v64, v92, v65
	v_add_f32_e32 v65, 1.0, v67
	v_rcp_f32_e32 v65, v65
	v_mul_f32_e32 v64, v76, v64
	v_cvt_pk_bf16_f32 v64, v64, s0
	v_add_u32_e32 v66, 0x4d000, v96
	global_store_short v66, v64, s[64:65]
	v_mul_f32_e32 v64, v93, v65
	v_mul_f32_e32 v65, 0xbfb8aa3b, v94
	v_exp_f32_e32 v65, v65
	v_mul_f32_e32 v67, 0xbfb8aa3b, v95
	v_exp_f32_e32 v67, v67
	v_mul_f32_e32 v64, v77, v64
	v_add_f32_e32 v65, 1.0, v65
	v_rcp_f32_e32 v65, v65
	v_cvt_pk_bf16_f32 v64, v64, s0
	v_add_u32_e32 v66, 0x4e600, v96
	global_store_short v66, v64, s[64:65]
	v_mul_f32_e32 v64, v94, v65
	v_add_f32_e32 v65, 1.0, v67
	v_rcp_f32_e32 v65, v65
	v_mul_f32_e32 v64, v78, v64
	v_cvt_pk_bf16_f32 v64, v64, s0
	v_add_u32_e32 v66, 0x4fc00, v96
	global_store_short v66, v64, s[64:65]
	v_mul_f32_e32 v64, v95, v65
	v_mul_f32_e32 v65, 0xbfb8aa3b, v48
	v_exp_f32_e32 v65, v65
	v_mul_f32_e32 v67, 0xbfb8aa3b, v49
	v_exp_f32_e32 v67, v67
	v_mul_f32_e32 v64, v79, v64
	v_add_f32_e32 v65, 1.0, v65
	v_rcp_f32_e32 v65, v65
	v_cvt_pk_bf16_f32 v64, v64, s0
	v_add_u32_e32 v66, 0x51200, v96
	global_store_short v66, v64, s[64:65]
	v_mul_f32_e32 v48, v48, v65
	v_mul_f32_e32 v32, v32, v48
	v_add_f32_e32 v48, 1.0, v67
	v_rcp_f32_e32 v48, v48
	v_cvt_pk_bf16_f32 v32, v32, s0
	v_add_u32_e32 v64, 0x58000, v96
	global_store_short v64, v32, s[64:65]
	v_mul_f32_e32 v32, v49, v48
	v_mul_f32_e32 v48, 0xbfb8aa3b, v50
	v_exp_f32_e32 v48, v48
	v_mul_f32_e32 v49, 0xbfb8aa3b, v51
	v_exp_f32_e32 v49, v49
	v_mul_f32_e32 v32, v33, v32
	v_add_f32_e32 v48, 1.0, v48
	v_rcp_f32_e32 v48, v48
	v_cvt_pk_bf16_f32 v32, v32, s0
	v_add_u32_e32 v33, 0x59600, v96
	global_store_short v33, v32, s[64:65]
	v_add_f32_e32 v33, 1.0, v49
	v_rcp_f32_e32 v33, v33
	v_mul_f32_e32 v32, v50, v48
	v_mul_f32_e32 v32, v34, v32
	v_cvt_pk_bf16_f32 v32, v32, s0
	v_add_u32_e32 v34, 0x5ac00, v96
	global_store_short v34, v32, s[64:65]
	v_mul_f32_e32 v32, v51, v33
	v_mul_f32_e32 v33, 0xbfb8aa3b, v52
	v_exp_f32_e32 v33, v33
	v_mul_f32_e32 v32, v35, v32
	v_mul_f32_e32 v35, 0xbfb8aa3b, v53
	v_exp_f32_e32 v35, v35
	v_add_f32_e32 v33, 1.0, v33
	v_rcp_f32_e32 v33, v33
	v_cvt_pk_bf16_f32 v32, v32, s0
	v_add_u32_e32 v34, 0x5c200, v96
	global_store_short v34, v32, s[64:65]
	v_mul_f32_e32 v32, v52, v33
	v_add_f32_e32 v33, 1.0, v35
	v_rcp_f32_e32 v33, v33
	v_mul_f32_e32 v32, v36, v32
	v_cvt_pk_bf16_f32 v32, v32, s0
	v_add_u32_e32 v34, 0x63000, v96
	global_store_short v34, v32, s[64:65]
	v_mul_f32_e32 v32, v53, v33
	v_mul_f32_e32 v33, 0xbfb8aa3b, v54
	v_exp_f32_e32 v33, v33
	v_mul_f32_e32 v35, 0xbfb8aa3b, v55
	v_exp_f32_e32 v35, v35
	v_mul_f32_e32 v32, v37, v32
	v_add_f32_e32 v33, 1.0, v33
	v_rcp_f32_e32 v33, v33
	v_cvt_pk_bf16_f32 v32, v32, s0
	v_add_u32_e32 v34, 0x64600, v96
	global_store_short v34, v32, s[64:65]
	v_mul_f32_e32 v32, v54, v33
	v_add_f32_e32 v33, 1.0, v35
	v_rcp_f32_e32 v33, v33
	v_mul_f32_e32 v32, v38, v32
	v_cvt_pk_bf16_f32 v32, v32, s0
; DI u16 f2bf(float a) { return (u16)(pack2(a, 0.f) & 0xffffu); }
; DI float siluf(float x) { return x * __builtin_amdgcn_rcpf(1.f + __expf(-x)); }
; DI int crow(int i, int h) { return (i & 3) + 8 * (i >> 2) + 4 * h; }
; template <int EPI, int MB, int NWC>
; DI void gemm_epi(const Params& p, int l, f32x16 (&acc)[MB][2], const float* rs, int mt, int nt, int gofs,
;                  int wr, int wc, int lr, int lh) {
;     ...
; #pragma unroll
;     for (int mb = 0; mb < MB; ++mb)
; #pragma unroll
;       for (int i = 0; i < 16; ++i) {
;         const int row = mt * TM + wr * WRS + mb * 32 + crow(i, lh);
;         const float a = acc[mb][0][i], b = acc[mb][1][i];
;         *(u16*)((char*)p.P + (unsigned)((row * FFH + (nt * NWC + wc) * 32 + lr) * 2)) = f2bf(siluf(a) * b);
;       }
	v_add_u32_e32 v34, 0x65c00, v96
	global_store_short v34, v32, s[64:65]
	v_mul_f32_e32 v32, v55, v33
	v_mul_f32_e32 v33, 0xbfb8aa3b, v56
	v_exp_f32_e32 v33, v33
	v_mul_f32_e32 v35, 0xbfb8aa3b, v57
	v_exp_f32_e32 v35, v35
	v_mul_f32_e32 v32, v39, v32
	v_add_f32_e32 v33, 1.0, v33
	v_rcp_f32_e32 v33, v33
	v_cvt_pk_bf16_f32 v32, v32, s0
	v_add_u32_e32 v34, 0x67200, v96
	global_store_short v34, v32, s[64:65]
	v_mul_f32_e32 v32, v56, v33
	v_add_f32_e32 v33, 1.0, v35
	v_rcp_f32_e32 v33, v33
	v_mul_f32_e32 v32, v40, v32
	v_cvt_pk_bf16_f32 v32, v32, s0
	v_add_u32_e32 v34, 0x6e000, v96
	global_store_short v34, v32, s[64:65]
	v_mul_f32_e32 v32, v57, v33
	v_mul_f32_e32 v33, 0xbfb8aa3b, v58
	v_exp_f32_e32 v33, v33
	v_mul_f32_e32 v35, 0xbfb8aa3b, v59
	v_exp_f32_e32 v35, v35
	v_mul_f32_e32 v32, v41, v32
	v_add_f32_e32 v33, 1.0, v33
	v_rcp_f32_e32 v33, v33
	v_cvt_pk_bf16_f32 v32, v32, s0
	v_add_u32_e32 v34, 0x6f600, v96
	global_store_short v34, v32, s[64:65]
	v_mul_f32_e32 v32, v58, v33
	v_add_f32_e32 v33, 1.0, v35
	v_rcp_f32_e32 v33, v33
	v_mul_f32_e32 v32, v42, v32
	v_cvt_pk_bf16_f32 v32, v32, s0
	v_add_u32_e32 v34, 0x70c00, v96
	global_store_short v34, v32, s[64:65]
	v_mul_f32_e32 v32, v59, v33
	v_mul_f32_e32 v33, 0xbfb8aa3b, v60
	v_exp_f32_e32 v33, v33
	v_mul_f32_e32 v35, 0xbfb8aa3b, v61
	v_exp_f32_e32 v35, v35
	v_mul_f32_e32 v32, v43, v32
	v_add_f32_e32 v33, 1.0, v33
	v_rcp_f32_e32 v33, v33
	v_cvt_pk_bf16_f32 v32, v32, s0
	v_add_u32_e32 v34, 0x72200, v96
	global_store_short v34, v32, s[64:65]
	v_mul_f32_e32 v32, v60, v33
	v_add_f32_e32 v33, 1.0, v35
	v_rcp_f32_e32 v33, v33
	v_mul_f32_e32 v32, v44, v32
	v_cvt_pk_bf16_f32 v32, v32, s0
	v_add_u32_e32 v34, 0x79000, v96
	global_store_short v34, v32, s[64:65]
	v_mul_f32_e32 v32, v61, v33
	v_mul_f32_e32 v33, 0xbfb8aa3b, v62
	v_exp_f32_e32 v33, v33
	v_mul_f32_e32 v35, 0xbfb8aa3b, v63
	v_exp_f32_e32 v35, v35
	v_mul_f32_e32 v32, v45, v32
	v_add_f32_e32 v33, 1.0, v33
	v_rcp_f32_e32 v33, v33
	v_cvt_pk_bf16_f32 v32, v32, s0
	v_add_u32_e32 v34, 0x7a600, v96
	global_store_short v34, v32, s[64:65]
	v_mul_f32_e32 v32, v62, v33
	v_add_f32_e32 v33, 1.0, v35
	v_rcp_f32_e32 v33, v33
	v_mul_f32_e32 v32, v46, v32
	v_cvt_pk_bf16_f32 v32, v32, s0
	v_add_u32_e32 v34, 0x7bc00, v96
	global_store_short v34, v32, s[64:65]
	v_mul_f32_e32 v32, v63, v33
	v_mul_f32_e32 v33, 0xbfb8aa3b, v16
	v_exp_f32_e32 v33, v33
	v_mul_f32_e32 v35, 0xbfb8aa3b, v17
	v_exp_f32_e32 v35, v35
	v_mul_f32_e32 v32, v47, v32
	v_add_f32_e32 v33, 1.0, v33
	v_rcp_f32_e32 v33, v33
	v_cvt_pk_bf16_f32 v32, v32, s0
	v_add_u32_e32 v34, 0x7d200, v96
	global_store_short v34, v32, s[64:65]
	v_mul_f32_e32 v16, v16, v33
	v_mul_f32_e32 v0, v0, v16
	v_add_f32_e32 v16, 1.0, v35
	v_rcp_f32_e32 v16, v16
	v_cvt_pk_bf16_f32 v0, v0, s0
	v_add_u32_e32 v32, 0x84000, v96
	global_store_short v32, v0, s[64:65]
	v_mul_f32_e32 v0, v17, v16
	v_mul_f32_e32 v16, 0xbfb8aa3b, v18
	v_exp_f32_e32 v16, v16
	v_mul_f32_e32 v17, 0xbfb8aa3b, v19
	v_exp_f32_e32 v17, v17
	v_mul_f32_e32 v0, v1, v0
	v_add_f32_e32 v16, 1.0, v16
	v_rcp_f32_e32 v16, v16
	v_cvt_pk_bf16_f32 v0, v0, s0
	v_add_u32_e32 v1, 0x85600, v96
	global_store_short v1, v0, s[64:65]
	v_add_f32_e32 v1, 1.0, v17
	v_rcp_f32_e32 v1, v1
	v_mul_f32_e32 v0, v18, v16
	v_mul_f32_e32 v0, v2, v0
	v_cvt_pk_bf16_f32 v0, v0, s0
	v_add_u32_e32 v2, 0x86c00, v96
	global_store_short v2, v0, s[64:65]
	v_mul_f32_e32 v0, v19, v1
	v_mul_f32_e32 v1, 0xbfb8aa3b, v20
	v_exp_f32_e32 v1, v1
	v_mul_f32_e32 v0, v3, v0
	v_mul_f32_e32 v3, 0xbfb8aa3b, v21
	v_exp_f32_e32 v3, v3
	v_add_f32_e32 v1, 1.0, v1
	v_rcp_f32_e32 v1, v1
	v_cvt_pk_bf16_f32 v0, v0, s0
	v_add_u32_e32 v2, 0x88200, v96
	global_store_short v2, v0, s[64:65]
	v_mul_f32_e32 v0, v20, v1
	v_add_f32_e32 v1, 1.0, v3
	v_rcp_f32_e32 v1, v1
	v_mul_f32_e32 v0, v4, v0
	v_cvt_pk_bf16_f32 v0, v0, s0
	v_add_u32_e32 v2, 0x8f000, v96
	global_store_short v2, v0, s[64:65]
	v_mul_f32_e32 v0, v21, v1
	v_mul_f32_e32 v1, 0xbfb8aa3b, v22
	v_exp_f32_e32 v1, v1
	v_mul_f32_e32 v3, 0xbfb8aa3b, v23
	v_exp_f32_e32 v3, v3
	v_mul_f32_e32 v0, v5, v0
	v_add_f32_e32 v1, 1.0, v1
	v_rcp_f32_e32 v1, v1
	v_cvt_pk_bf16_f32 v0, v0, s0
	v_add_u32_e32 v2, 0x90600, v96
	global_store_short v2, v0, s[64:65]
	v_mul_f32_e32 v0, v22, v1
	v_add_f32_e32 v1, 1.0, v3
	v_rcp_f32_e32 v1, v1
	v_mul_f32_e32 v0, v6, v0
	v_cvt_pk_bf16_f32 v0, v0, s0
	v_add_u32_e32 v2, 0x91c00, v96
	global_store_short v2, v0, s[64:65]
	v_mul_f32_e32 v0, v23, v1
	v_mul_f32_e32 v1, 0xbfb8aa3b, v24
	v_exp_f32_e32 v1, v1
	v_mul_f32_e32 v3, 0xbfb8aa3b, v25
	v_exp_f32_e32 v3, v3
	v_mul_f32_e32 v0, v7, v0
	v_add_f32_e32 v1, 1.0, v1
	v_rcp_f32_e32 v1, v1
	v_cvt_pk_bf16_f32 v0, v0, s0
	v_add_u32_e32 v2, 0x93200, v96
	global_store_short v2, v0, s[64:65]
	v_mul_f32_e32 v0, v24, v1
	v_add_f32_e32 v1, 1.0, v3
	v_rcp_f32_e32 v1, v1
	v_mul_f32_e32 v0, v8, v0
	v_cvt_pk_bf16_f32 v0, v0, s0
	v_add_u32_e32 v2, 0x9a000, v96
	global_store_short v2, v0, s[64:65]
	v_mul_f32_e32 v0, v25, v1
; DI u16 f2bf(float a) { return (u16)(pack2(a, 0.f) & 0xffffu); }
; DI float siluf(float x) { return x * __builtin_amdgcn_rcpf(1.f + __expf(-x)); }
; DI int crow(int i, int h) { return (i & 3) + 8 * (i >> 2) + 4 * h; }
; template <int EPI, int MB, int NWC>
; DI void gemm_epi(const Params& p, int l, f32x16 (&acc)[MB][2], const float* rs, int mt, int nt, int gofs,
;                  int wr, int wc, int lr, int lh) {
;     ...
; #pragma unroll
;     for (int mb = 0; mb < MB; ++mb)
; #pragma unroll
;       for (int i = 0; i < 16; ++i) {
;         const int row = mt * TM + wr * WRS + mb * 32 + crow(i, lh);
;         const float a = acc[mb][0][i], b = acc[mb][1][i];
;         *(u16*)((char*)p.P + (unsigned)((row * FFH + (nt * NWC + wc) * 32 + lr) * 2)) = f2bf(siluf(a) * b);
;       }
; template <int EPI, bool RSQ>
; DI void gemm_phase8(const Params& p, int l, const u16* __restrict__ A, int lda, const u16* __restrict__ Bt, int K,
;                    int ntiles_n, int gofs, char* smem, bool latonly = false) {
;     ...
; #pragma unroll
;       for (int a = 0; a < 4; ++a)
; #pragma unroll
;         for (int b = 0; b < 2; ++b)
; #pragma unroll
;           for (int i = 0; i < 16; ++i) acc[a][b][i] = 0.f;
;     }
;     if (Sset_valid) stash(Sa, Sb, cur ^ 1);
;     __syncthreads();
;     cur ^= 1;
;     if (last) {
;       t += nlb;
;       if (t >= total) return false;
;       decode(t, mt, nt);
;       kt = 0;
;     } else {
;       ++kt;
;     }
;     return true;
	v_mul_f32_e32 v1, 0xbfb8aa3b, v26
	v_exp_f32_e32 v1, v1
	v_mul_f32_e32 v3, 0xbfb8aa3b, v27
	v_exp_f32_e32 v3, v3
	v_mul_f32_e32 v0, v9, v0
	v_add_f32_e32 v1, 1.0, v1
	v_rcp_f32_e32 v1, v1
	v_cvt_pk_bf16_f32 v0, v0, s0
	v_add_u32_e32 v2, 0x9b600, v96
	global_store_short v2, v0, s[64:65]
	v_mul_f32_e32 v0, v26, v1
	v_add_f32_e32 v1, 1.0, v3
	v_rcp_f32_e32 v1, v1
	v_mul_f32_e32 v0, v10, v0
	v_cvt_pk_bf16_f32 v0, v0, s0
	v_add_u32_e32 v2, 0x9cc00, v96
	global_store_short v2, v0, s[64:65]
	v_mul_f32_e32 v0, v27, v1
	v_mul_f32_e32 v1, 0xbfb8aa3b, v28
	v_exp_f32_e32 v1, v1
	v_mul_f32_e32 v3, 0xbfb8aa3b, v29
	v_exp_f32_e32 v3, v3
	v_mul_f32_e32 v0, v11, v0
	v_add_f32_e32 v1, 1.0, v1
	v_rcp_f32_e32 v1, v1
	v_cvt_pk_bf16_f32 v0, v0, s0
	v_add_u32_e32 v2, 0x9e200, v96
	global_store_short v2, v0, s[64:65]
	v_mul_f32_e32 v0, v28, v1
	v_add_f32_e32 v1, 1.0, v3
	v_rcp_f32_e32 v1, v1
	v_mul_f32_e32 v0, v12, v0
	v_cvt_pk_bf16_f32 v0, v0, s0
	v_add_u32_e32 v2, 0xa5000, v96
	global_store_short v2, v0, s[64:65]
	v_mul_f32_e32 v0, v29, v1
	v_mul_f32_e32 v1, 0xbfb8aa3b, v30
	v_exp_f32_e32 v1, v1
	v_mul_f32_e32 v3, 0xbfb8aa3b, v31
	v_exp_f32_e32 v3, v3
	v_mul_f32_e32 v0, v13, v0
	v_add_f32_e32 v1, 1.0, v1
	v_rcp_f32_e32 v1, v1
	v_cvt_pk_bf16_f32 v0, v0, s0
	v_add_u32_e32 v2, 0xa6600, v96
	global_store_short v2, v0, s[64:65]
	v_mul_f32_e32 v0, v30, v1
	v_add_f32_e32 v1, 1.0, v3
	v_rcp_f32_e32 v1, v1
	v_mul_f32_e32 v0, v14, v0
	v_cvt_pk_bf16_f32 v0, v0, s0
	v_add_u32_e32 v2, 0xa7c00, v96
	global_store_short v2, v0, s[64:65]
	v_mul_f32_e32 v0, v31, v1
	v_mul_f32_e32 v0, v15, v0
	v_cvt_pk_bf16_f32 v0, v0, s0
	v_add_u32_e32 v1, 0xa9200, v96
	global_store_short v1, v0, s[64:65]
	v_mov_b32_e32 v0, 0
	global_store_short v96, v162, s[64:65]
	v_mov_b32_e32 v1, v0
	v_mov_b32_e32 v2, v0
	v_mov_b32_e32 v3, v0
	v_mov_b32_e32 v4, v0
	v_mov_b32_e32 v5, v0
	v_mov_b32_e32 v6, v0
	v_mov_b32_e32 v7, v0
	v_mov_b32_e32 v8, v0
	v_mov_b32_e32 v9, v0
	v_mov_b32_e32 v10, v0
	v_mov_b32_e32 v11, v0
	v_mov_b32_e32 v12, v0
	v_mov_b32_e32 v13, v0
	v_mov_b32_e32 v14, v0
	v_mov_b32_e32 v15, v0
	v_mov_b32_e32 v16, v0
	v_mov_b32_e32 v17, v0
	v_mov_b32_e32 v18, v0
	v_mov_b32_e32 v19, v0
	v_mov_b32_e32 v20, v0
	v_mov_b32_e32 v21, v0
	v_mov_b32_e32 v22, v0
	v_mov_b32_e32 v23, v0
	v_mov_b32_e32 v24, v0
	v_mov_b32_e32 v25, v0
	v_mov_b32_e32 v26, v0
	v_mov_b32_e32 v27, v0
	v_mov_b32_e32 v28, v0
	v_mov_b32_e32 v29, v0
	v_mov_b32_e32 v30, v0
	v_mov_b32_e32 v31, v0
	v_mov_b32_e32 v32, v0
	v_mov_b32_e32 v33, v0
	v_mov_b32_e32 v34, v0
	v_mov_b32_e32 v35, v0
	v_mov_b32_e32 v36, v0
	v_mov_b32_e32 v37, v0
	v_mov_b32_e32 v38, v0
	v_mov_b32_e32 v39, v0
	v_mov_b32_e32 v40, v0
	v_mov_b32_e32 v41, v0
	v_mov_b32_e32 v42, v0
	v_mov_b32_e32 v43, v0
	v_mov_b32_e32 v44, v0
	v_mov_b32_e32 v45, v0
	v_mov_b32_e32 v46, v0
	v_mov_b32_e32 v47, v0
	v_mov_b32_e32 v48, v0
	v_mov_b32_e32 v49, v0
	v_mov_b32_e32 v50, v0
	v_mov_b32_e32 v51, v0
	v_mov_b32_e32 v52, v0
	v_mov_b32_e32 v53, v0
	v_mov_b32_e32 v54, v0
	v_mov_b32_e32 v55, v0
	v_mov_b32_e32 v56, v0
	v_mov_b32_e32 v57, v0
	v_mov_b32_e32 v58, v0
	v_mov_b32_e32 v59, v0
	v_mov_b32_e32 v60, v0
	v_mov_b32_e32 v61, v0
	v_mov_b32_e32 v62, v0
	v_mov_b32_e32 v63, v0
	v_mov_b32_e32 v64, v0
	v_mov_b32_e32 v65, v0
	v_mov_b32_e32 v66, v0
	v_mov_b32_e32 v67, v0
	v_mov_b32_e32 v68, v0
	v_mov_b32_e32 v69, v0
	v_mov_b32_e32 v70, v0
	v_mov_b32_e32 v71, v0
	v_mov_b32_e32 v72, v0
	v_mov_b32_e32 v73, v0
	v_mov_b32_e32 v74, v0
	v_mov_b32_e32 v75, v0
	v_mov_b32_e32 v76, v0
	v_mov_b32_e32 v77, v0
	v_mov_b32_e32 v78, v0
	v_mov_b32_e32 v79, v0
	v_mov_b32_e32 v80, v0
	v_mov_b32_e32 v81, v0
	v_mov_b32_e32 v82, v0
	v_mov_b32_e32 v83, v0
	v_mov_b32_e32 v84, v0
	v_mov_b32_e32 v85, v0
	v_mov_b32_e32 v86, v0
	v_mov_b32_e32 v87, v0
	v_mov_b32_e32 v88, v0
	v_mov_b32_e32 v89, v0
	v_mov_b32_e32 v90, v0
	v_mov_b32_e32 v91, v0
	v_mov_b32_e32 v92, v0
	v_mov_b32_e32 v93, v0
	v_mov_b32_e32 v94, v0
	v_mov_b32_e32 v95, v0
	v_mov_b32_e32 v96, v0
	v_mov_b32_e32 v97, v0
	v_mov_b32_e32 v98, v0
	v_mov_b32_e32 v99, v0
	v_mov_b32_e32 v100, v0
	v_mov_b32_e32 v101, v0
	v_mov_b32_e32 v102, v0
	v_mov_b32_e32 v103, v0
	v_mov_b32_e32 v104, v0
	v_mov_b32_e32 v105, v0
	v_mov_b32_e32 v106, v0
	v_mov_b32_e32 v107, v0
	v_mov_b32_e32 v108, v0
	v_mov_b32_e32 v109, v0
	v_mov_b32_e32 v110, v0
	v_mov_b32_e32 v111, v0
	v_mov_b32_e32 v112, v0
	v_mov_b32_e32 v113, v0
	v_mov_b32_e32 v114, v0
	v_mov_b32_e32 v115, v0
	v_mov_b32_e32 v116, v0
	v_mov_b32_e32 v117, v0
	v_mov_b32_e32 v118, v0
	v_mov_b32_e32 v119, v0
	v_mov_b32_e32 v120, v0
	v_mov_b32_e32 v121, v0
	v_mov_b32_e32 v122, v0
	v_mov_b32_e32 v123, v0
	v_mov_b32_e32 v124, v0
	v_mov_b32_e32 v125, v0
	v_mov_b32_e32 v126, v0
	v_mov_b32_e32 v127, v0
.LBB1_1446:
	s_and_b64 vcc, exec, s[2:3]
	s_xor_b32 s12, s12, 1
	s_cbranch_vccnz .LBB1_1448
.LBB1_1448:
	s_mov_b64 s[2:3], -1
	s_and_b64 vcc, exec, s[8:9]
	s_waitcnt lgkmcnt(0)
	s_barrier
	s_cbranch_vccz .LBB1_1450
	s_add_i32 s17, s17, 1
	s_mov_b64 s[2:3], 0

; template <int EPI, bool RSQ>
; DI void gemm_phase8(const Params& p, int l, const u16* __restrict__ A, int lda, const u16* __restrict__ Bt, int K,
;                    int ntiles_n, int gofs, char* smem, bool latonly = false) {
;     ...
;   unsigned LAo = (unsigned)((mt * 256 + srow) * lda + sch * 8) * 2u;
;   unsigned LBo = (unsigned)((nt * 256 + srow) * K + sch * 8) * 2u;
;   const unsigned strideA = (unsigned)(64 * lda) * 2u, strideB = (unsigned)(64 * K) * 2u;
;   auto issue = [&](u32x4 (&qa)[4], u32x4 (&qb)[4]) {
; #pragma unroll
;     for (int i = 0; i < 4; ++i) {
;       qa[i] = *(const u32x4*)((const char*)A + (LAo + i * strideA + (unsigned)Lkt * 128u));
;       qb[i] = *(const u32x4*)((const char*)Bt + (LBo + i * strideB + (unsigned)Lkt * 128u));
;     }
;     if (++Lkt == nk) {
;       Lkt = 0; Lt += nlb;
;       if (Lt < total) {
;         int a, b; decode(Lt, a, b);
;         LAo = (unsigned)((a * 256 + srow) * lda + sch * 8) * 2u;
;         LBo = (unsigned)((b * 256 + srow) * K + sch * 8) * 2u;
;       } else Lvalid = false;
;     }
;   };
;   float ssq[4] = {0.f, 0.f, 0.f, 0.f};
;   auto stash = [&](u32x4 (&qa)[4], u32x4 (&qb)[4], int stage) {
;     char* As = smem + stage * 73728;
;     char* Bs = As + 36864;
; #pragma unroll
;     for (int i = 0; i < 4; ++i) {
;       if (RSQ) { float f[8]; unpack8(qa[i], f);
; #pragma unroll
;         for (int e = 0; e < 8; ++e) ssq[i] = fmaf(f[e], f[e], ssq[i]); }
;       *(u32x4*)(As + (srow + 64 * i) * 144 + sch * 16) = qa[i];
;       *(u32x4*)(Bs + (srow + 64 * i) * 144 + sch * 16) = qb[i];
;     }
;   };
;   auto stash_part = [&](u32x4 (&qa)[4], u32x4 (&qb)[4], int stage, int i) {
;     char* As = smem + stage * 73728;
;     char* Bs = As + 36864;
;     if (RSQ) { float f[8]; unpack8(qa[i], f);
; #pragma unroll
;       for (int e = 0; e < 8; ++e) ssq[i] = fmaf(f[e], f[e], ssq[i]); }
;     *(u32x4*)(As + (srow + 64 * i) * 144 + sch * 16) = qa[i];
;     *(u32x4*)(Bs + (srow + 64 * i) * 144 + sch * 16) = qb[i];
;   };
;   u32x4 ra0[4], rb0[4], ra1[4], rb1[4];
;   f32x16 acc[4][2];
; #pragma unroll
;   for (int a = 0; a < 4; ++a)
; #pragma unroll
;     for (int b = 0; b < 2; ++b)
; #pragma unroll
;       for (int i = 0; i < 16; ++i) acc[a][b][i] = 0.f;
;   issue(ra0, rb0);
;   bool v1 = DEEP && Lvalid;
;   if (v1) issue(ra1, rb1);
;   stash(ra0, rb0, 0);
;   __syncthreads();
.LBB1_1509:
	v_ashrrev_i32_e32 v1, 3, v0
	v_lshlrev_b32_e32 v2, 4, v0
	v_and_b32_e32 v194, 0x70, v2
	v_lshl_add_u32 v2, s16, 8, v1
	v_readlane_b32 s0, v235, 59
	v_mul_lo_u32 v2, v2, s30
	v_readlane_b32 s1, v235, 60
	s_add_u32 s0, s0, 0x1390000
	v_or_b32_e32 v214, v2, v194
	v_readlane_b32 s3, v236, 54
	s_addc_u32 s1, s1, 0
	v_add_u32_e32 v2, 0x108000, v214
	s_add_i32 s17, s2, s3
	v_add_u32_e32 v3, 0xb0000, v214
	global_load_dwordx4 v[128:131], v2, s[0:1]
	global_load_dwordx4 v[140:143], v3, s[0:1]
	v_lshl_add_u32 v2, s17, 8, v1
	v_mul_lo_u32 v2, v2, s30
	v_or_b32_e32 v216, v2, v194
	v_add_u32_e32 v3, 0x58000, v214
	v_add_u32_e32 v4, 0x58000, v216
	v_add_u32_e32 v2, 0x108000, v216
	global_load_dwordx4 v[136:139], v214, s[0:1]
	global_load_dwordx4 v[132:135], v216, s[64:65]
	global_load_dwordx4 v[144:147], v3, s[0:1]
	v_add_u32_e32 v3, 0xb0000, v216
	global_load_dwordx4 v[148:151], v4, s[64:65]
	global_load_dwordx4 v[152:155], v3, s[64:65]
	global_load_dwordx4 v[156:159], v2, s[64:65]
	v_ashrrev_i32_e32 v199, 8, v0
	v_and_b32_e32 v201, 31, v0
	v_and_b32_e32 v200, 0xc0, v0
	v_bfe_u32 v202, v0, 5, 1
	v_and_b32_e32 v2, 0xdf, v0
	v_mov_b32_e32 v0, 0
	v_readlane_b32 s22, v235, 17
	v_mul_lo_u32 v16, v1, s47
	v_lshl_or_b32 v17, v199, 7, v201
	s_mov_b32 s31, 1
	s_mov_b32 s18, 0
	s_mov_b64 s[4:5], -1
	s_mov_b32 s19, s22
	s_mov_b32 s23, 0
	v_lshlrev_b32_e32 v203, 4, v202
	v_mul_u32_u24_e32 v213, 0x90, v2
	v_lshlrev_b32_e32 v215, 1, v1
	v_mov_b32_e32 v1, v0
	v_mov_b32_e32 v2, v0
	v_mov_b32_e32 v3, v0
	v_mov_b32_e32 v4, v0
	v_mov_b32_e32 v5, v0
	v_mov_b32_e32 v6, v0
	v_mov_b32_e32 v7, v0
	v_mov_b32_e32 v8, v0
	v_mov_b32_e32 v9, v0
	v_mov_b32_e32 v10, v0
	v_mov_b32_e32 v11, v0
	v_mov_b32_e32 v12, v0
	v_mov_b32_e32 v13, v0
	v_mov_b32_e32 v14, v0
	v_mov_b32_e32 v15, v0
	v_mov_b32_e32 v64, v0
	v_mov_b32_e32 v65, v0
	v_mov_b32_e32 v66, v0
	v_mov_b32_e32 v67, v0
	v_mov_b32_e32 v68, v0
	v_mov_b32_e32 v69, v0
	v_mov_b32_e32 v70, v0
	v_mov_b32_e32 v71, v0
	v_mov_b32_e32 v72, v0
	v_mov_b32_e32 v73, v0
	v_mov_b32_e32 v74, v0
	v_mov_b32_e32 v75, v0
	v_mov_b32_e32 v76, v0
	v_mov_b32_e32 v77, v0
	v_mov_b32_e32 v78, v0
	v_mov_b32_e32 v79, v0
	v_add3_u32 v217, 0, v16, v194
	v_mul_lo_u32 v218, v17, s47
	v_mov_b32_e32 v16, v0
	v_mov_b32_e32 v17, v0
	v_mov_b32_e32 v18, v0
	v_mov_b32_e32 v19, v0
	v_mov_b32_e32 v20, v0
	v_mov_b32_e32 v21, v0
	v_mov_b32_e32 v22, v0
	v_mov_b32_e32 v23, v0
	v_mov_b32_e32 v24, v0
	v_mov_b32_e32 v25, v0
	v_mov_b32_e32 v26, v0
	v_mov_b32_e32 v27, v0
	v_mov_b32_e32 v28, v0
	v_mov_b32_e32 v29, v0
	v_mov_b32_e32 v30, v0
	v_mov_b32_e32 v31, v0
	v_mov_b32_e32 v80, v0
	v_mov_b32_e32 v81, v0
	v_mov_b32_e32 v82, v0
	v_mov_b32_e32 v83, v0
	v_mov_b32_e32 v84, v0
	v_mov_b32_e32 v85, v0
	v_mov_b32_e32 v86, v0
	v_mov_b32_e32 v87, v0
	v_mov_b32_e32 v88, v0
	v_mov_b32_e32 v89, v0
	v_mov_b32_e32 v90, v0
	v_mov_b32_e32 v91, v0
	v_mov_b32_e32 v92, v0
	v_mov_b32_e32 v93, v0
	v_mov_b32_e32 v94, v0
	v_mov_b32_e32 v95, v0
	v_mov_b32_e32 v32, v0
	v_mov_b32_e32 v33, v0
	v_mov_b32_e32 v34, v0
	v_mov_b32_e32 v35, v0
	v_mov_b32_e32 v36, v0
	v_mov_b32_e32 v37, v0
	v_mov_b32_e32 v38, v0
	v_mov_b32_e32 v39, v0
	v_mov_b32_e32 v40, v0
	v_mov_b32_e32 v41, v0
	v_mov_b32_e32 v42, v0
	v_mov_b32_e32 v43, v0
	v_mov_b32_e32 v44, v0
	v_mov_b32_e32 v45, v0
	v_mov_b32_e32 v46, v0
	v_mov_b32_e32 v47, v0
	v_mov_b32_e32 v96, v0
	v_mov_b32_e32 v97, v0
	v_mov_b32_e32 v98, v0
	v_mov_b32_e32 v99, v0
	v_mov_b32_e32 v100, v0
	v_mov_b32_e32 v101, v0
	v_mov_b32_e32 v102, v0
	v_mov_b32_e32 v103, v0
	v_mov_b32_e32 v104, v0
	v_mov_b32_e32 v105, v0
	v_mov_b32_e32 v106, v0
	v_mov_b32_e32 v107, v0
	v_mov_b32_e32 v108, v0
	v_mov_b32_e32 v109, v0
	v_mov_b32_e32 v110, v0
	v_mov_b32_e32 v111, v0
	v_mov_b32_e32 v48, v0
	v_mov_b32_e32 v49, v0
	v_mov_b32_e32 v50, v0
	v_mov_b32_e32 v51, v0
	v_mov_b32_e32 v52, v0
	v_mov_b32_e32 v53, v0
	v_mov_b32_e32 v54, v0
	v_mov_b32_e32 v55, v0
	v_mov_b32_e32 v56, v0
	v_mov_b32_e32 v57, v0
	v_mov_b32_e32 v58, v0
	v_mov_b32_e32 v59, v0
	v_mov_b32_e32 v60, v0
	v_mov_b32_e32 v61, v0
	v_mov_b32_e32 v62, v0
	v_mov_b32_e32 v63, v0
	v_mov_b32_e32 v112, v0
	v_mov_b32_e32 v113, v0
	v_mov_b32_e32 v114, v0
	v_mov_b32_e32 v115, v0
	v_mov_b32_e32 v116, v0
	v_mov_b32_e32 v117, v0
	v_mov_b32_e32 v118, v0
	v_mov_b32_e32 v119, v0
	s_waitcnt vmcnt(20)
	v_mov_b32_e32 v120, v0
	v_mov_b32_e32 v121, v0
	v_mov_b32_e32 v122, v0
	v_mov_b32_e32 v123, v0
	s_waitcnt vmcnt(19)
	v_mov_b32_e32 v124, v0
	v_mov_b32_e32 v125, v0
	v_mov_b32_e32 v126, v0
	v_mov_b32_e32 v127, v0
	s_waitcnt vmcnt(5)
	ds_write_b128 v217, v[136:139] offset:36864
	s_waitcnt vmcnt(4)
	ds_write_b128 v217, v[132:135]
	s_waitcnt vmcnt(3)
	ds_write_b128 v217, v[144:147] offset:46080
	ds_write_b128 v217, v[140:143] offset:55296
	ds_write_b128 v217, v[128:131] offset:64512
	s_waitcnt vmcnt(2)
	ds_write_b128 v217, v[148:151] offset:9216
	s_waitcnt vmcnt(1)
	ds_write_b128 v217, v[152:155] offset:18432
	s_waitcnt vmcnt(0)
	ds_write_b128 v217, v[156:159] offset:27648
	s_lshl_b32 s4, s31, 7
	s_waitcnt vmcnt(0)
	v_add_u32_e32 v128, s4, v216
	v_add_u32_e32 v129, s4, v214
	v_add_u32_e32 v130, 0x58000, v128
	global_load_dwordx4 v[148:151], v130, s[64:65]
	v_add_u32_e32 v130, 0x58000, v129
	global_load_dwordx4 v[132:135], v128, s[64:65]
	global_load_dwordx4 v[136:139], v129, s[0:1]
	global_load_dwordx4 v[144:147], v130, s[0:1]
	v_add_u32_e32 v130, 0xb0000, v128
	v_add_u32_e32 v128, 0x108000, v128
	global_load_dwordx4 v[152:155], v130, s[64:65]
	v_add_u32_e32 v130, 0xb0000, v129
	global_load_dwordx4 v[156:159], v128, s[64:65]
	v_add_u32_e32 v128, 0x108000, v129
	global_load_dwordx4 v[140:143], v130, s[0:1]
	s_add_i32 s31, s31, 1
	global_load_dwordx4 v[128:131], v128, s[0:1]
	s_cmp_lg_u32 s31, 44
	s_mov_b64 s[4:5], -1
	s_waitcnt lgkmcnt(0)
	s_barrier
	s_branch .LBB1_1512

; template <int EPI, bool RSQ>
; DI void gemm_phase8(const Params& p, int l, const u16* __restrict__ A, int lda, const u16* __restrict__ Bt, int K,
;                    int ntiles_n, int gofs, char* smem, bool latonly = false) {
;     ...
;   auto issue = [&](u32x4 (&qa)[4], u32x4 (&qb)[4]) {
; #pragma unroll
;     for (int i = 0; i < 4; ++i) {
;       qa[i] = *(const u32x4*)((const char*)A + (LAo + i * strideA + (unsigned)Lkt * 128u));
;     ...
;     {
;       const char* As = smem + cur * 73728;
;       const char* Bs = As + 36864;
;       const char* ap = As + (wr * 128 + lr) * 144 + lh * 16;
;       const char* bp = Bs + (wc * 64 + lr) * 144 + lh * 16;
;       bf16x8 fa[3][2], fb[2][2];
;       fa[0][0] = *(const bf16x8*)(ap);
;       fa[0][1] = *(const bf16x8*)(ap + 32 * 144);
;       fb[0][0] = *(const bf16x8*)(bp);
;       fb[0][1] = *(const bf16x8*)(bp + 32 * 144);
;       fa[1][0] = *(const bf16x8*)(ap + 2 * 32 * 144);
;       fa[1][1] = *(const bf16x8*)(ap + 3 * 32 * 144);
;       fb[1][0] = *(const bf16x8*)(bp + 32);
;       fb[1][1] = *(const bf16x8*)(bp + 32 * 144 + 32);
; #pragma unroll
;       for (int u = 0; u < 8; ++u) {
;         const int ks = u >> 1, hf = u & 1, ca = u % 3, cb = ks & 1;
;         if (u + 2 < 8) {
;           const int ks2 = (u + 2) >> 1, hf2 = (u + 2) & 1, cn = (u + 2) % 3;
;           fa[cn][0] = *(const bf16x8*)(ap + (2 * hf2) * 32 * 144 + ks2 * 32);
;           fa[cn][1] = *(const bf16x8*)(ap + (2 * hf2 + 1) * 32 * 144 + ks2 * 32);
;         }
;         __builtin_amdgcn_sched_barrier(0);
;         __builtin_amdgcn_s_setprio(1);
;         acc[2 * hf][0] = MFMA32(fa[ca][0], fb[cb][0], acc[2 * hf][0]);
;         acc[2 * hf][1] = MFMA32(fa[ca][0], fb[cb][1], acc[2 * hf][1]);
;         acc[2 * hf + 1][0] = MFMA32(fa[ca][1], fb[cb][0], acc[2 * hf + 1][0]);
;         acc[2 * hf + 1][1] = MFMA32(fa[ca][1], fb[cb][1], acc[2 * hf + 1][1]);
;         __builtin_amdgcn_s_setprio(0);
;         __builtin_amdgcn_sched_barrier(0);
;         if (u == 0) {
;           if (Lset_valid) issue(La, Lb);
;           __builtin_amdgcn_sched_barrier(0);
;         }
;         if (hf == 1 && ks + 2 < 4) {
;           fb[cb][0] = *(const bf16x8*)(bp + (ks + 2) * 32);
;           fb[cb][1] = *(const bf16x8*)(bp + 32 * 144 + (ks + 2) * 32);
;           __builtin_amdgcn_sched_barrier(0);
;         }
;       }
.LBB1_1512:
	s_mul_i32 s2, s18, 0x12000
	s_add_i32 s2, s2, 0
	v_add_u32_e32 v160, s2, v218
	v_add_u32_e32 v219, v160, v203
	v_add_u32_e32 v160, s2, v213
	v_add_u32_e32 v220, v160, v203
	ds_read_b128 v[176:179], v220 offset:36864
	ds_read_b128 v[160:163], v220 offset:36896
	ds_read_b128 v[188:191], v219 offset:9216
	ds_read_b128 v[180:183], v219 offset:13824
	ds_read_b128 v[184:187], v220 offset:41472
	ds_read_b128 v[164:167], v220 offset:41504
	ds_read_b128 v[222:225], v219
	ds_read_b128 v[172:175], v219 offset:32
	ds_read_b128 v[226:229], v219 offset:4608
	ds_read_b128 v[168:171], v219 offset:4640
	v_subrev_u32_e32 v238, s2, v217
	v_add_u32_e32 v238, 0x12000, v238
	s_setprio 1
	s_waitcnt lgkmcnt(3)
	v_mfma_f32_32x32x16_bf16 v[112:127], v[222:225], v[176:179], v[112:127]
	v_mfma_f32_32x32x16_bf16 v[48:63], v[222:225], v[184:187], v[48:63]
	s_waitcnt lgkmcnt(1)
	v_mfma_f32_32x32x16_bf16 v[96:111], v[226:229], v[176:179], v[96:111]
	v_mfma_f32_32x32x16_bf16 v[32:47], v[226:229], v[184:187], v[32:47]
	s_setprio 0
.LBB1_1519:
	ds_read_b128 v[222:225], v219 offset:9248
	ds_read_b128 v[226:229], v219 offset:13856
	s_setprio 1
	v_mfma_f32_32x32x16_bf16 v[80:95], v[188:191], v[176:179], v[80:95]
	v_mfma_f32_32x32x16_bf16 v[16:31], v[188:191], v[184:187], v[16:31]
	v_mfma_f32_32x32x16_bf16 v[64:79], v[180:183], v[176:179], v[64:79]
	v_mfma_f32_32x32x16_bf16 v[0:15], v[180:183], v[184:187], v[0:15]
	s_setprio 0
	ds_read_b128 v[176:179], v220 offset:36928
	ds_read_b128 v[180:183], v220 offset:41536
	ds_read_b128 v[184:187], v219 offset:64
	ds_read_b128 v[188:191], v219 offset:4672
	s_setprio 1
	v_mfma_f32_32x32x16_bf16 v[112:127], v[172:175], v[160:163], v[112:127]
	v_mfma_f32_32x32x16_bf16 v[48:63], v[172:175], v[164:167], v[48:63]
	s_waitcnt lgkmcnt(6)
	v_mfma_f32_32x32x16_bf16 v[96:111], v[168:171], v[160:163], v[96:111]
	v_mfma_f32_32x32x16_bf16 v[32:47], v[168:171], v[164:167], v[32:47]
	s_setprio 0
	ds_read_b128 v[168:171], v219 offset:9280
	ds_read_b128 v[172:175], v219 offset:13888
	s_setprio 1
	s_waitcnt lgkmcnt(7)
	v_mfma_f32_32x32x16_bf16 v[80:95], v[222:225], v[160:163], v[80:95]
	v_mfma_f32_32x32x16_bf16 v[16:31], v[222:225], v[164:167], v[16:31]
	s_waitcnt lgkmcnt(6)
	v_mfma_f32_32x32x16_bf16 v[64:79], v[226:229], v[160:163], v[64:79]
	v_mfma_f32_32x32x16_bf16 v[0:15], v[226:229], v[164:167], v[0:15]
	s_setprio 0
	ds_read_b128 v[160:163], v220 offset:36960
	ds_read_b128 v[164:167], v220 offset:41568
	ds_read_b128 v[220:223], v219 offset:96
	ds_read_b128 v[224:227], v219 offset:4704
	s_setprio 1
	s_waitcnt lgkmcnt(7)
	v_mfma_f32_32x32x16_bf16 v[112:127], v[184:187], v[176:179], v[112:127]
	v_mfma_f32_32x32x16_bf16 v[48:63], v[184:187], v[180:183], v[48:63]
	s_waitcnt lgkmcnt(6)
	v_mfma_f32_32x32x16_bf16 v[96:111], v[188:191], v[176:179], v[96:111]
	v_mfma_f32_32x32x16_bf16 v[32:47], v[188:191], v[180:183], v[32:47]
	s_setprio 0
	ds_read_b128 v[184:187], v219 offset:9312
	ds_read_b128 v[188:191], v219 offset:13920
	s_waitcnt vmcnt(6)
	ds_write_b128 v238, v[148:151] offset:9216
	ds_write_b128 v238, v[132:135]
	s_setprio 1
	s_waitcnt lgkmcnt(9)
	v_mfma_f32_32x32x16_bf16 v[80:95], v[168:171], v[176:179], v[80:95]
	v_mfma_f32_32x32x16_bf16 v[16:31], v[168:171], v[180:183], v[16:31]
	s_waitcnt lgkmcnt(8)
	v_mfma_f32_32x32x16_bf16 v[64:79], v[172:175], v[176:179], v[64:79]
	v_mfma_f32_32x32x16_bf16 v[0:15], v[172:175], v[180:183], v[0:15]
	s_setprio 0
	s_waitcnt vmcnt(3)
	ds_write_b128 v238, v[136:139] offset:36864
	ds_write_b128 v238, v[144:147] offset:46080
	ds_write_b128 v238, v[152:155] offset:18432
	s_setprio 1
	s_waitcnt lgkmcnt(8)
	v_mfma_f32_32x32x16_bf16 v[112:127], v[220:223], v[160:163], v[112:127]
	v_mfma_f32_32x32x16_bf16 v[48:63], v[220:223], v[164:167], v[48:63]
	s_waitcnt lgkmcnt(7)
	v_mfma_f32_32x32x16_bf16 v[96:111], v[224:227], v[160:163], v[96:111]
	v_mfma_f32_32x32x16_bf16 v[32:47], v[224:227], v[164:167], v[32:47]
	s_setprio 0
	s_waitcnt vmcnt(0)
	ds_write_b128 v238, v[156:159] offset:27648
	ds_write_b128 v238, v[140:143] offset:55296
	ds_write_b128 v238, v[128:131] offset:64512
	s_setprio 1
	s_waitcnt lgkmcnt(9)
	v_mfma_f32_32x32x16_bf16 v[80:95], v[184:187], v[160:163], v[80:95]
	v_mfma_f32_32x32x16_bf16 v[16:31], v[184:187], v[164:167], v[16:31]
	s_waitcnt lgkmcnt(8)
	v_mfma_f32_32x32x16_bf16 v[64:79], v[188:191], v[160:163], v[64:79]
	v_mfma_f32_32x32x16_bf16 v[0:15], v[188:191], v[164:167], v[0:15]
	s_setprio 0
	v_cndmask_b32_e64 v221, 0, 1, s[4:5]
	v_cmp_ne_u32_e64 s[2:3], 1, v221
	s_andn2_b64 vcc, exec, s[4:5]
	s_mov_b64 s[4:5], 0
	s_cbranch_vccnz .Lgemm_issue_done_4
	s_lshl_b32 s4, s31, 7
	s_waitcnt vmcnt(0)
	v_add_u32_e32 v128, s4, v216
	v_add_u32_e32 v129, s4, v214
	v_add_u32_e32 v130, 0x58000, v128
	global_load_dwordx4 v[148:151], v130, s[64:65]
	v_add_u32_e32 v130, 0x58000, v129
	global_load_dwordx4 v[132:135], v128, s[64:65]
	global_load_dwordx4 v[136:139], v129, s[0:1]
	global_load_dwordx4 v[144:147], v130, s[0:1]
	v_add_u32_e32 v130, 0xb0000, v128
	v_add_u32_e32 v128, 0x108000, v128
	global_load_dwordx4 v[152:155], v130, s[64:65]
	v_add_u32_e32 v130, 0xb0000, v129
	global_load_dwordx4 v[156:159], v128, s[64:65]
	v_add_u32_e32 v128, 0x108000, v129
	global_load_dwordx4 v[140:143], v130, s[0:1]
	s_add_i32 s31, s31, 1
	global_load_dwordx4 v[128:131], v128, s[0:1]
	s_cmp_lg_u32 s31, 44
	s_mov_b64 s[4:5], -1
	s_cbranch_scc1 .Lgemm_issue_done_4
	v_readlane_b32 s4, v236, 44
	s_add_i32 s19, s19, s4
	s_cmp_ge_i32 s19, s21
	s_mov_b64 s[4:5], 0
	s_cbranch_scc1 .LBB1_1518
	s_ashr_i32 s4, s19, 31
	s_lshr_b32 s4, s4, 27
	s_add_i32 s4, s19, s4
	s_ashr_i32 s5, s4, 5
	s_lshl_b32 s5, s5, 3
	s_sub_i32 s6, s20, s5
	s_min_i32 s6, s6, 8
	s_abs_i32 s7, s6
	v_cvt_f32_u32_e32 v214, s7
	s_sub_i32 s10, 0, s7
	s_andn2_b32 s4, s4, 31
	s_sub_i32 s8, s19, s4
	v_rcp_iflag_f32_e32 v214, v214
	s_abs_i32 s4, s8
	s_xor_b32 s9, s8, s6
	s_ashr_i32 s9, s9, 31
	v_mul_f32_e32 v214, 0x4f7ffffe, v214
	v_cvt_u32_f32_e32 v214, v214
	s_nop 0
	v_readfirstlane_b32 s11, v214
	s_mul_i32 s10, s10, s11
	s_mul_hi_u32 s10, s11, s10
	s_add_i32 s11, s11, s10
	s_mul_hi_u32 s10, s4, s11
	s_mul_i32 s11, s10, s7
	s_sub_i32 s4, s4, s11
	s_add_i32 s12, s10, 1
	s_sub_i32 s11, s4, s7
	s_cmp_ge_u32 s4, s7
	s_cselect_b32 s10, s12, s10
	s_cselect_b32 s4, s11, s4
	s_add_i32 s11, s10, 1
	s_cmp_ge_u32 s4, s7
	s_cselect_b32 s4, s11, s10
	s_xor_b32 s4, s4, s9
	s_sub_i32 s4, s4, s9
	s_mul_i32 s6, s4, s6
	s_sub_i32 s6, s8, s6
	s_and_b64 vcc, exec, s[40:41]
	s_add_i32 s5, s6, s5
	s_cbranch_vccnz .LBB1_1517
	s_ashr_i32 s6, s5, 4
	s_mul_i32 s6, s6, 17
	s_and_b32 s5, s5, 15
	s_add_i32 s5, s5, s6
	s_add_i32 s5, s5, 1

; template <int EPI, int MB, int NWC>
; DI void gemm_epi(const Params& p, int l, f32x16 (&acc)[MB][2], const float* rs, int mt, int nt, int gofs,
;                  int wr, int wc, int lr, int lh) {
;     ...
;   } else if (EPI == EPI_RES) {
;     float* Hout = isctx ? p.Hc + ((size_t)bidx * CTXL + tt0) * DM : p.Hl + ((size_t)bidx * SEQ + tt0 - CTXL) * DM;
;     const float* gate = p.mod + ((size_t)l * 17 + (isctx ? 16 : bidx)) * 6144 + gofs;
; #pragma unroll
;     for (int nb = 0; nb < 2; ++nb) {
;       const int col = nt * TN + wc * 64 + nb * 32 + lr;
;       const float gv = gate[col];
; template <int EPI, bool RSQ>
; DI void gemm_phase8(const Params& p, int l, const u16* __restrict__ A, int lda, const u16* __restrict__ Bt, int K,
;                    int ntiles_n, int gofs, char* smem, bool latonly = false) {
;     ...
;     if (last) {
;       if (RSQ) {
; #pragma unroll
;         for (int i = 0; i < 4; ++i) {
;           float v = ssq[i];
;           v += dpp_f<0xB1>(v); v += dpp_f<0x4E>(v); v += dpp_f<0x141>(v);
;           if (sch == 0) rs[srow + 64 * i] = rsqrtf(v / (float)K + 1e-6f);
;           ssq[i] = 0.f;
;         }
;         __syncthreads();
;       }
;       gemm_epi<EPI, 4, 4>(p, l, acc, rs, mt, nt, gofs, wr, wc, lr, lh);
.Lgemm_issue_done_4:
	s_cmp_lg_u32 s23, 43
	s_cselect_b64 s[6:7], -1, 0
	s_and_b64 vcc, exec, s[6:7]
	s_cbranch_vccnz .LBB1_1525
	s_mul_hi_i32 s8, s17, 0x78787879
	s_lshr_b32 s9, s8, 31
	s_ashr_i32 s8, s8, 3
	s_add_i32 s10, s8, s9
	s_mul_i32 s8, s10, 17
	s_sub_i32 s8, s17, s8
	s_lshl_b32 s12, s8, 8
	s_ashr_i32 s11, s10, 31
	v_mov_b32_e32 v160, v201
	v_mov_b32_e32 v161, v202
	v_mov_b32_e32 v162, v199
	s_cmp_gt_i32 s8, 0
	s_mov_b64 s[14:15], -1
	s_cbranch_scc0 .LBB1_1522
	s_lshl_b64 s[8:9], s[10:11], 24
	s_mov_b32 s13, s97
	s_add_u32 s14, s50, s8
	s_addc_u32 s15, s51, s9
	s_lshl_b64 s[8:9], s[12:13], 12
	s_add_u32 s8, s14, s8
	s_addc_u32 s9, s15, s9
	s_add_u32 s8, s8, 0xfff00000
	s_addc_u32 s9, s9, -1
	s_mov_b64 s[14:15], 0

; template <int EPI, bool RSQ>
; DI void gemm_phase8(const Params& p, int l, const u16* __restrict__ A, int lda, const u16* __restrict__ Bt, int K,
;                    int ntiles_n, int gofs, char* smem, bool latonly = false) {
;     ...
;     if (Sset_valid) stash(Sa, Sb, cur ^ 1);
;     __syncthreads();
;     cur ^= 1;
;     if (last) {
;       t += nlb;
;       if (t >= total) return false;
;       decode(t, mt, nt);
;       kt = 0;
;     } else {
;       ++kt;
;     }
;     return true;
.LBB1_1525:
	s_and_b64 vcc, exec, s[2:3]
	s_xor_b32 s18, s18, 1
	s_cbranch_vccnz .LBB1_1527
.LBB1_1527:
	s_mov_b64 s[2:3], -1
	s_and_b64 vcc, exec, s[6:7]
	s_waitcnt lgkmcnt(0)
	s_barrier
	s_cbranch_vccz .LBB1_1529
	s_add_i32 s23, s23, 1
	s_mov_b64 s[2:3], 0
